# p7 and p3-gate epilogues: all loads of an iteration issued up front (counted / single wait instead of one exposed round trip per element group)
# speedup vs baseline: 1.1263x; 1.0101x over previous
; DEVI float sigmoidf_(float x) { return 1.f / (1.f + __expf(-x)); }
; DEVI void gate_tile(const Params& P, int l, int pm, int q, char* smem, int tid) {
;     ...
;   for (int q = 0; q < 8; ++q) {
;     const int id = tid + 256 * q, row = id >> 4, g4 = id & 15;
;     const int cl = g4 * 4, wcc = cl >> 5, c32 = cl & 31;
;     const long grow = (long)pm * 128 + row;
;     const int col = nb * 128 + hb * 64 + cl;
;     float4 rp = *reinterpret_cast<const float4*>(T + row * 128 + wcc * 64 + c32);
;     float4 gp = *reinterpret_cast<const float4*>(T + row * 128 + wcc * 64 + 32 + c32);
;     float xv[4], bav[4], bxv[4], lmv[4];
;     load4bf(cb + grow * 1024 + col, xv);
;     ld4f(ba + col, bav); ld4f(bx + col, bxv); ld4f(lam + col, lmv);
;     const float rpa[4] = {rp.x, rp.y, rp.z, rp.w}, gpa[4] = {gp.x, gp.y, gp.z, gp.w};
;     float av[4], uv[4];
; #pragma unroll
;     for (int i = 0; i < 4; ++i) {
;       float r = sigmoidf_(rpa[i] + bav[i]);
;       float gi = sigmoidf_(gpa[i] + bxv[i]);
;       float a = __expf(-8.f * log1pf(__expf(-lmv[i])) * r);
;       av[i] = a;
;       uv[i] = sqrtf(fmaxf(1.f - a * a, 0.f)) * gi * xv[i];
;     }
;     *reinterpret_cast<float4*>(au0 + grow * 1024 + col) = make_float4(av[0], av[1], av[2], av[3]);
;     *reinterpret_cast<float4*>(au1 + grow * 1024 + col) = make_float4(uv[0], uv[1], uv[2], uv[3]);
;     *reinterpret_cast<float4*>(Tw + row * 128 + wcc * 64 + c32) = make_float4(av[0], av[1], av[2], av[3]);
;     *reinterpret_cast<float4*>(Tw + row * 128 + wcc * 64 + 32 + c32) = make_float4(uv[0], uv[1], uv[2], uv[3]);
.LBB0_459:
	v_add_u32_e32 v173, s61, v20
	v_ashrrev_i32_e32 v170, 4, v173
	v_ashrrev_i32_e32 v171, 31, v170
	v_lshlrev_b64 v[170:171], 10, v[170:171]
	v_lshl_add_u64 v[174:175], v[170:171], 0, s[54:55]
	v_lshl_add_u64 v[170:171], v[174:175], 1, v[48:49]
	global_load_dwordx2 v[208:209], v[170:171], off
	global_load_dwordx4 v[212:215], v[50:51], off
	global_load_dwordx4 v[216:219], v[52:53], off
	global_load_dwordx4 v[220:223], v[54:55], off
	v_add_u32_e32 v175, s61, v20
	v_add_u32_e32 v170, 0x100, v175
	v_ashrrev_i32_e32 v172, 4, v170
	v_ashrrev_i32_e32 v173, 31, v172
	v_lshlrev_b64 v[172:173], 10, v[172:173]
	v_lshl_add_u64 v[176:177], v[172:173], 0, s[54:55]
	v_lshl_add_u64 v[172:173], v[176:177], 1, v[48:49]
	global_load_dwordx2 v[210:211], v[172:173], off
	v_add_u32_e32 v175, s61, v20
	v_add_u32_e32 v170, 0x200, v175
	v_ashrrev_i32_e32 v172, 4, v170
	v_ashrrev_i32_e32 v173, 31, v172
	v_lshlrev_b64 v[172:173], 10, v[172:173]
	v_lshl_add_u64 v[176:177], v[172:173], 0, s[54:55]
	v_lshl_add_u64 v[172:173], v[176:177], 1, v[48:49]
	global_load_dwordx2 v[224:225], v[172:173], off
	v_add_u32_e32 v175, s61, v20
	v_add_u32_e32 v170, 0x300, v175
	v_ashrrev_i32_e32 v172, 4, v170
	v_ashrrev_i32_e32 v173, 31, v172
	v_lshlrev_b64 v[172:173], 10, v[172:173]
	v_lshl_add_u64 v[176:177], v[172:173], 0, s[54:55]
	v_lshl_add_u64 v[172:173], v[176:177], 1, v[48:49]
	global_load_dwordx2 v[226:227], v[172:173], off
	s_waitcnt vmcnt(0)
	v_add_u32_e32 v41, s61, v20
	v_ashrrev_i32_e32 v8, 4, v41
	v_ashrrev_i32_e32 v9, 31, v8
	v_lshl_or_b32 v43, v8, 9, v112
	v_lshlrev_b64 v[8:9], 10, v[8:9]
	v_lshl_add_u64 v[100:101], v[8:9], 0, s[54:55]
	v_lshl_add_u64 v[8:9], v[100:101], 1, v[48:49]
	ds_read_b128 v[4:7], v43
	ds_read_b128 v[0:3], v43 offset:128
	v_mov_b32_e32 v8, v208
	v_mov_b32_e32 v9, v209
	s_addk_i32 s61, 0x400
	s_cmpk_eq_i32 s61, 0x800
	v_lshlrev_b32_e32 v62, 16, v8
	v_and_b32_e32 v63, 0xffff0000, v8
	v_lshlrev_b32_e32 v60, 16, v9
	v_and_b32_e32 v61, 0xffff0000, v9
	v_mov_b32_e32 v16, v212
	v_mov_b32_e32 v17, v213
	v_mov_b32_e32 v18, v214
	v_mov_b32_e32 v19, v215
	v_mov_b32_e32 v12, v216
	v_mov_b32_e32 v13, v217
	v_mov_b32_e32 v14, v218
	v_mov_b32_e32 v15, v219
	v_mov_b32_e32 v8, v220
	v_mov_b32_e32 v9, v221
	v_mov_b32_e32 v10, v222
	v_mov_b32_e32 v11, v223
	s_waitcnt lgkmcnt(1)
	v_add_f32_e32 v4, v4, v16
	v_mul_f32_e32 v4, 0xbfb8aa3b, v4
	v_exp_f32_e32 v4, v4
	s_waitcnt lgkmcnt(0)
	v_add_f32_e32 v0, v0, v12
	v_mul_f32_e32 v0, 0xbfb8aa3b, v0
	v_add_f32_e32 v5, v5, v17
	v_add_f32_e32 v4, 1.0, v4
	v_div_scale_f32 v16, s[46:47], v4, v4, 1.0
	v_rcp_f32_e32 v45, v16
	v_mul_f32_e32 v5, 0xbfb8aa3b, v5
	v_exp_f32_e32 v5, v5
	v_add_f32_e32 v1, v1, v13
	v_fma_f32 v47, -v16, v45, 1.0
	v_fmac_f32_e32 v45, v47, v45
	v_div_scale_f32 v47, vcc, 1.0, v4, 1.0
	v_mul_f32_e32 v113, v47, v45
	v_fma_f32 v114, -v16, v113, v47
	v_fmac_f32_e32 v113, v114, v45
	v_fma_f32 v16, -v16, v113, v47
	v_div_fmas_f32 v16, v16, v45, v113
	v_div_fixup_f32 v16, v16, v4, 1.0
	v_exp_f32_e32 v4, v0
	v_add_f32_e32 v5, 1.0, v5
	v_mul_f32_e32 v1, 0xbfb8aa3b, v1
	v_add_f32_e32 v6, v6, v18
	v_mul_f32_e32 v6, 0xbfb8aa3b, v6
	v_exp_f32_e32 v6, v6
	s_nop 0
	v_add_f32_e32 v6, 1.0, v6
	v_add_f32_e32 v2, v2, v14
	v_mul_f32_e32 v2, 0xbfb8aa3b, v2
	v_add_f32_e32 v7, v7, v19
	v_mul_f32_e32 v7, 0xbfb8aa3b, v7
	v_exp_f32_e32 v7, v7
	v_mov_b32_e32 v0, v240
	v_mul_f32_e32 v0, v16, v0
	v_mul_f32_e32 v0, 0x3fb8aa3b, v0
	v_exp_f32_e32 v0, v0
	v_add_f32_e32 v7, 1.0, v7
	v_add_f32_e32 v3, v3, v15
	v_mul_f32_e32 v3, 0xbfb8aa3b, v3
	v_fma_f32 v8, -v0, v0, 1.0
	v_max_f32_e32 v8, 0, v8
	v_cmp_gt_f32_e32 vcc, s69, v8
	v_mul_f32_e32 v12, 0x4f800000, v8
	s_nop 0
	v_cndmask_b32_e32 v8, v8, v12, vcc
	v_sqrt_f32_e32 v12, v8
	s_nop 0
	v_add_u32_e32 v16, -1, v12
	v_fma_f32 v45, -v16, v12, v8
	v_cmp_ge_f32_e64 s[46:47], 0, v45
	v_add_u32_e32 v45, 1, v12
	s_nop 0
	v_cndmask_b32_e64 v16, v12, v16, s[46:47]
	v_fma_f32 v12, -v45, v12, v8
	v_cmp_lt_f32_e64 s[46:47], 0, v12
	s_nop 1
	v_cndmask_b32_e64 v12, v16, v45, s[46:47]
	v_mul_f32_e32 v16, 0x37800000, v12
	v_cndmask_b32_e32 v12, v12, v16, vcc
	v_cmp_class_f32_e32 vcc, v8, v186
	s_nop 1
	v_cndmask_b32_e32 v8, v12, v8, vcc
	v_div_scale_f32 v12, s[46:47], v5, v5, 1.0
	v_rcp_f32_e32 v16, v12
	s_nop 0
	v_fma_f32 v17, -v12, v16, 1.0
	v_fmac_f32_e32 v16, v17, v16
	v_div_scale_f32 v17, vcc, 1.0, v5, 1.0
	v_mul_f32_e32 v45, v17, v16
	v_fma_f32 v47, -v12, v45, v17
	v_fmac_f32_e32 v45, v47, v16
	v_fma_f32 v12, -v12, v45, v17
	v_div_fmas_f32 v12, v12, v16, v45
	v_div_fixup_f32 v16, v12, v5, 1.0
	v_exp_f32_e32 v5, v1
	s_nop 0
	v_pk_add_f32 v[4:5], v[4:5], 1.0 op_sel_hi:[1,0]
	s_nop 1
	s_nop 1
	s_nop 1
	v_mov_b32_e32 v1, v241
	v_mul_f32_e32 v1, v16, v1
	v_mul_f32_e32 v1, 0x3fb8aa3b, v1
	v_exp_f32_e32 v1, v1
	s_nop 0
	v_fma_f32 v9, -v1, v1, 1.0
	v_max_f32_e32 v9, 0, v9
	v_cmp_gt_f32_e32 vcc, s69, v9
	v_mul_f32_e32 v12, 0x4f800000, v9
	s_nop 0
	v_cndmask_b32_e32 v9, v9, v12, vcc
	v_sqrt_f32_e32 v12, v9
	s_nop 0
	v_add_u32_e32 v13, -1, v12
	v_fma_f32 v16, -v13, v12, v9
	v_cmp_ge_f32_e64 s[46:47], 0, v16
	v_add_u32_e32 v16, 1, v12
	s_nop 0
	v_cndmask_b32_e64 v13, v12, v13, s[46:47]
	v_fma_f32 v12, -v16, v12, v9
	v_cmp_lt_f32_e64 s[46:47], 0, v12
	s_nop 1
	v_cndmask_b32_e64 v12, v13, v16, s[46:47]
	v_mul_f32_e32 v13, 0x37800000, v12
	v_cndmask_b32_e32 v12, v12, v13, vcc
	v_cmp_class_f32_e32 vcc, v9, v186
	s_nop 1
	v_cndmask_b32_e32 v9, v12, v9, vcc
	v_div_scale_f32 v12, s[46:47], v6, v6, 1.0
	v_rcp_f32_e32 v13, v12
	s_nop 0
	v_fma_f32 v16, -v12, v13, 1.0
	v_fmac_f32_e32 v13, v16, v13
	v_div_scale_f32 v16, vcc, 1.0, v6, 1.0
	v_mul_f32_e32 v17, v16, v13
	v_fma_f32 v18, -v12, v17, v16
	v_fmac_f32_e32 v17, v18, v13
; DEVI float sigmoidf_(float x) { return 1.f / (1.f + __expf(-x)); }
; DEVI void gate_tile(const Params& P, int l, int pm, int q, char* smem, int tid) {
;     ...
;       float r = sigmoidf_(rpa[i] + bav[i]);
;       float gi = sigmoidf_(gpa[i] + bxv[i]);
;       float a = __expf(-8.f * log1pf(__expf(-lmv[i])) * r);
;       av[i] = a;
;       uv[i] = sqrtf(fmaxf(1.f - a * a, 0.f)) * gi * xv[i];
;     }
;     *reinterpret_cast<float4*>(au0 + grow * 1024 + col) = make_float4(av[0], av[1], av[2], av[3]);
;     *reinterpret_cast<float4*>(au1 + grow * 1024 + col) = make_float4(uv[0], uv[1], uv[2], uv[3]);
;     *reinterpret_cast<float4*>(Tw + row * 128 + wcc * 64 + c32) = make_float4(av[0], av[1], av[2], av[3]);
;     *reinterpret_cast<float4*>(Tw + row * 128 + wcc * 64 + 32 + c32) = make_float4(uv[0], uv[1], uv[2], uv[3]);
	v_fma_f32 v12, -v12, v17, v16
	v_div_fmas_f32 v12, v12, v13, v17
	v_div_fixup_f32 v16, v12, v6, 1.0
	v_exp_f32_e32 v6, v2
	s_nop 0
	s_nop 1
	s_nop 1
	s_nop 1
	v_mov_b32_e32 v2, v242
	v_mul_f32_e32 v2, v16, v2
	v_mul_f32_e32 v2, 0x3fb8aa3b, v2
	v_exp_f32_e32 v2, v2
	s_nop 0
	v_fma_f32 v10, -v2, v2, 1.0
	v_max_f32_e32 v10, 0, v10
	v_cmp_gt_f32_e32 vcc, s69, v10
	v_mul_f32_e32 v12, 0x4f800000, v10
	s_nop 0
	v_cndmask_b32_e32 v10, v10, v12, vcc
	v_sqrt_f32_e32 v12, v10
	s_nop 0
	v_add_u32_e32 v13, -1, v12
	v_fma_f32 v14, -v13, v12, v10
	v_cmp_ge_f32_e64 s[46:47], 0, v14
	v_add_u32_e32 v14, 1, v12
	s_nop 0
	v_cndmask_b32_e64 v13, v12, v13, s[46:47]
	v_fma_f32 v12, -v14, v12, v10
	v_cmp_lt_f32_e64 s[46:47], 0, v12
	s_nop 1
	v_cndmask_b32_e64 v12, v13, v14, s[46:47]
	v_mul_f32_e32 v13, 0x37800000, v12
	v_cndmask_b32_e32 v12, v12, v13, vcc
	v_cmp_class_f32_e32 vcc, v10, v186
	s_nop 1
	v_cndmask_b32_e32 v10, v12, v10, vcc
	v_div_scale_f32 v12, s[46:47], v7, v7, 1.0
	v_rcp_f32_e32 v13, v12
	s_nop 0
	v_fma_f32 v14, -v12, v13, 1.0
	v_fmac_f32_e32 v13, v14, v13
	v_div_scale_f32 v14, vcc, 1.0, v7, 1.0
	v_mul_f32_e32 v16, v14, v13
	v_fma_f32 v17, -v12, v16, v14
	v_fmac_f32_e32 v16, v17, v13
	v_fma_f32 v12, -v12, v16, v14
	v_div_fmas_f32 v12, v12, v13, v16
	v_div_fixup_f32 v14, v12, v7, 1.0
	v_exp_f32_e32 v7, v3
	s_nop 0
	v_pk_add_f32 v[6:7], v[6:7], 1.0 op_sel_hi:[1,0]
	s_nop 1
	s_nop 1
	s_nop 1
	v_mov_b32_e32 v3, v243
	v_mul_f32_e32 v3, v14, v3
	v_mul_f32_e32 v3, 0x3fb8aa3b, v3
	v_exp_f32_e32 v3, v3
	s_nop 0
	v_fma_f32 v11, -v3, v3, 1.0
	v_max_f32_e32 v11, 0, v11
	v_cmp_gt_f32_e32 vcc, s69, v11
	v_mul_f32_e32 v12, 0x4f800000, v11
	s_nop 0
	v_cndmask_b32_e32 v11, v11, v12, vcc
	v_sqrt_f32_e32 v12, v11
	s_nop 0
	v_add_u32_e32 v13, -1, v12
	v_fma_f32 v14, -v13, v12, v11
	v_cmp_ge_f32_e64 s[46:47], 0, v14
	v_add_u32_e32 v14, 1, v12
	s_nop 0
	v_cndmask_b32_e64 v13, v12, v13, s[46:47]
	v_fma_f32 v12, -v14, v12, v11
	v_cmp_lt_f32_e64 s[46:47], 0, v12
	s_nop 1
	v_cndmask_b32_e64 v12, v13, v14, s[46:47]
	v_mul_f32_e32 v13, 0x37800000, v12
	v_cndmask_b32_e32 v12, v12, v13, vcc
	v_cmp_class_f32_e32 vcc, v11, v186
	s_nop 1
	v_cndmask_b32_e32 v11, v12, v11, vcc
	v_lshlrev_b64 v[12:13], 2, v[100:101]
	v_lshl_add_u64 v[14:15], v[56:57], 0, v[12:13]
	global_store_dwordx4 v[14:15], v[0:3], off
	v_div_scale_f32 v14, s[46:47], v5, v5, 1.0
	v_rcp_f32_e32 v15, v14
	v_lshl_add_u64 v[12:13], v[58:59], 0, v[12:13]
	v_fma_f32 v16, -v14, v15, 1.0
	v_fmac_f32_e32 v15, v16, v15
	v_div_scale_f32 v16, vcc, 1.0, v5, 1.0
	v_mul_f32_e32 v17, v16, v15
	v_fma_f32 v18, -v14, v17, v16
	v_fmac_f32_e32 v17, v18, v15
	v_fma_f32 v14, -v14, v17, v16
	v_div_fmas_f32 v14, v14, v15, v17
	v_div_fixup_f32 v5, v14, v5, 1.0
	v_div_scale_f32 v14, s[46:47], v4, v4, 1.0
	v_rcp_f32_e32 v15, v14
	s_nop 0
	v_fma_f32 v16, -v14, v15, 1.0
	v_fmac_f32_e32 v15, v16, v15
	v_div_scale_f32 v16, vcc, 1.0, v4, 1.0
	v_mul_f32_e32 v17, v16, v15
	v_fma_f32 v18, -v14, v17, v16
	v_fmac_f32_e32 v17, v18, v15
	v_fma_f32 v14, -v14, v17, v16
	v_div_fmas_f32 v14, v14, v15, v17
	v_div_fixup_f32 v4, v14, v4, 1.0
	v_pk_mul_f32 v[4:5], v[4:5], v[8:9]
	v_div_scale_f32 v8, s[46:47], v7, v7, 1.0
	v_rcp_f32_e32 v9, v8
	v_pk_mul_f32 v[4:5], v[4:5], v[62:63]
	v_fma_f32 v14, -v8, v9, 1.0
	v_fmac_f32_e32 v9, v14, v9
	v_div_scale_f32 v14, vcc, 1.0, v7, 1.0
	v_mul_f32_e32 v15, v14, v9
	v_fma_f32 v16, -v8, v15, v14
	v_fmac_f32_e32 v15, v16, v9
	v_fma_f32 v8, -v8, v15, v14
	v_div_fmas_f32 v8, v8, v9, v15
	v_div_fixup_f32 v7, v8, v7, 1.0
	v_div_scale_f32 v8, s[46:47], v6, v6, 1.0
	v_rcp_f32_e32 v9, v8
	s_nop 0
	v_fma_f32 v14, -v8, v9, 1.0
	v_fmac_f32_e32 v9, v14, v9
	v_div_scale_f32 v14, vcc, 1.0, v6, 1.0
	v_mul_f32_e32 v15, v14, v9
	v_fma_f32 v16, -v8, v15, v14
	v_fmac_f32_e32 v15, v16, v9
	v_fma_f32 v8, -v8, v15, v14
	v_div_fmas_f32 v8, v8, v9, v15
	v_div_fixup_f32 v6, v8, v6, 1.0
	v_pk_mul_f32 v[6:7], v[6:7], v[10:11]
	s_nop 0
	v_pk_mul_f32 v[6:7], v[6:7], v[60:61]
	global_store_dwordx4 v[12:13], v[4:7], off
	ds_write_b128 v43, v[0:3]
	ds_write_b128 v43, v[4:7] offset:128
	v_add_u32_e32 v0, 0x100, v41
	v_ashrrev_i32_e32 v4, 4, v0
	v_ashrrev_i32_e32 v5, 31, v4
	v_lshl_or_b32 v43, v4, 9, v112
	v_lshlrev_b64 v[4:5], 10, v[4:5]
	v_lshl_add_u64 v[100:101], v[4:5], 0, s[54:55]
	v_lshl_add_u64 v[4:5], v[100:101], 1, v[48:49]
	ds_read_b128 v[12:15], v43
	ds_read_b128 v[0:3], v43 offset:128
	v_mov_b32_e32 v4, v210
	v_mov_b32_e32 v5, v211
	v_lshlrev_b32_e32 v62, 16, v4
	v_and_b32_e32 v63, 0xffff0000, v4
	v_lshlrev_b32_e32 v60, 16, v5
	v_and_b32_e32 v61, 0xffff0000, v5
	v_mov_b32_e32 v16, v212
	v_mov_b32_e32 v17, v213
	v_mov_b32_e32 v18, v214
	v_mov_b32_e32 v19, v215
	v_mov_b32_e32 v8, v216
	v_mov_b32_e32 v9, v217
	v_mov_b32_e32 v10, v218
	v_mov_b32_e32 v11, v219
	v_mov_b32_e32 v4, v220
	v_mov_b32_e32 v5, v221
	v_mov_b32_e32 v6, v222
	v_mov_b32_e32 v7, v223
	s_waitcnt lgkmcnt(1)
	v_add_f32_e32 v12, v12, v16
	v_mul_f32_e32 v12, 0xbfb8aa3b, v12
	v_exp_f32_e32 v12, v12
	s_waitcnt lgkmcnt(0)
; DEVI float sigmoidf_(float x) { return 1.f / (1.f + __expf(-x)); }
; DEVI void gate_tile(const Params& P, int l, int pm, int q, char* smem, int tid) {
;     ...
;     for (int i = 0; i < 4; ++i) {
;       float r = sigmoidf_(rpa[i] + bav[i]);
;       float gi = sigmoidf_(gpa[i] + bxv[i]);
;       float a = __expf(-8.f * log1pf(__expf(-lmv[i])) * r);
;       av[i] = a;
;       uv[i] = sqrtf(fmaxf(1.f - a * a, 0.f)) * gi * xv[i];
;     }
	v_add_f32_e32 v0, v0, v8
	v_mul_f32_e32 v0, 0xbfb8aa3b, v0
	v_exp_f32_e32 v8, v0
	v_add_f32_e32 v12, 1.0, v12
	v_div_scale_f32 v16, s[46:47], v12, v12, 1.0
	v_rcp_f32_e32 v45, v16
	v_add_f32_e32 v1, v1, v9
	v_fma_f32 v47, -v16, v45, 1.0
	v_fmac_f32_e32 v45, v47, v45
	v_div_scale_f32 v47, vcc, 1.0, v12, 1.0
	v_mul_f32_e32 v113, v47, v45
	v_fma_f32 v114, -v16, v113, v47
	v_fmac_f32_e32 v113, v114, v45
	v_fma_f32 v16, -v16, v113, v47
	v_div_fmas_f32 v16, v16, v45, v113
	v_div_fixup_f32 v12, v16, v12, 1.0
	v_mul_f32_e32 v1, 0xbfb8aa3b, v1
	v_exp_f32_e32 v9, v1
	v_add_f32_e32 v2, v2, v10
	v_mul_f32_e32 v2, 0xbfb8aa3b, v2
	v_exp_f32_e32 v10, v2
	v_mov_b32_e32 v0, v240
	v_mul_f32_e32 v0, v12, v0
	v_mul_f32_e32 v0, 0x3fb8aa3b, v0
	v_exp_f32_e32 v0, v0
	v_add_f32_e32 v3, v3, v11
	v_fma_f32 v4, -v0, v0, 1.0
	v_max_f32_e32 v4, 0, v4
	v_cmp_gt_f32_e32 vcc, s69, v4
	v_mul_f32_e32 v12, 0x4f800000, v4
	s_nop 0
	v_cndmask_b32_e32 v4, v4, v12, vcc
	v_sqrt_f32_e32 v12, v4
	v_mul_f32_e32 v3, 0xbfb8aa3b, v3
	v_exp_f32_e32 v11, v3
	v_add_u32_e32 v16, -1, v12
	v_fma_f32 v45, -v16, v12, v4
	v_cmp_ge_f32_e64 s[46:47], 0, v45
	v_add_u32_e32 v45, 1, v12
	s_nop 0
	v_cndmask_b32_e64 v16, v12, v16, s[46:47]
	v_fma_f32 v12, -v45, v12, v4
	v_cmp_lt_f32_e64 s[46:47], 0, v12
	v_pk_add_f32 v[8:9], v[8:9], 1.0 op_sel_hi:[1,0]
	s_nop 0
	v_cndmask_b32_e64 v12, v16, v45, s[46:47]
	v_mul_f32_e32 v16, 0x37800000, v12
	v_cndmask_b32_e32 v12, v12, v16, vcc
	v_cmp_class_f32_e32 vcc, v4, v186
	s_nop 1
	v_cndmask_b32_e32 v4, v12, v4, vcc
	v_add_f32_e32 v12, v13, v17
	v_mul_f32_e32 v12, 0xbfb8aa3b, v12
	v_exp_f32_e32 v12, v12
	s_nop 0
	v_add_f32_e32 v12, 1.0, v12
	v_div_scale_f32 v13, s[46:47], v12, v12, 1.0
	v_rcp_f32_e32 v16, v13
	s_nop 0
	v_fma_f32 v17, -v13, v16, 1.0
	v_fmac_f32_e32 v16, v17, v16
	v_div_scale_f32 v17, vcc, 1.0, v12, 1.0
	v_mul_f32_e32 v45, v17, v16
	v_fma_f32 v47, -v13, v45, v17
	v_fmac_f32_e32 v45, v47, v16
	v_fma_f32 v13, -v13, v45, v17
	v_div_fmas_f32 v13, v13, v16, v45
	v_div_fixup_f32 v16, v13, v12, 1.0
	s_nop 1
	s_nop 1
	s_nop 1
	v_mov_b32_e32 v1, v241
	v_mul_f32_e32 v1, v16, v1
	v_mul_f32_e32 v1, 0x3fb8aa3b, v1
	v_exp_f32_e32 v1, v1
	s_nop 0
	v_fma_f32 v5, -v1, v1, 1.0
	v_max_f32_e32 v5, 0, v5
	v_cmp_gt_f32_e32 vcc, s69, v5
	v_mul_f32_e32 v12, 0x4f800000, v5
	s_nop 0
	v_cndmask_b32_e32 v5, v5, v12, vcc
	v_sqrt_f32_e32 v12, v5
	s_nop 0
	v_add_u32_e32 v13, -1, v12
	v_fma_f32 v16, -v13, v12, v5
	v_cmp_ge_f32_e64 s[46:47], 0, v16
	v_add_u32_e32 v16, 1, v12
	s_nop 0
	v_cndmask_b32_e64 v13, v12, v13, s[46:47]
	v_fma_f32 v12, -v16, v12, v5
	v_cmp_lt_f32_e64 s[46:47], 0, v12
	s_nop 1
	v_cndmask_b32_e64 v12, v13, v16, s[46:47]
	v_mul_f32_e32 v13, 0x37800000, v12
	v_cndmask_b32_e32 v12, v12, v13, vcc
	v_cmp_class_f32_e32 vcc, v5, v186
	s_nop 1
	v_cndmask_b32_e32 v5, v12, v5, vcc
	v_add_f32_e32 v12, v14, v18
	v_mul_f32_e32 v12, 0xbfb8aa3b, v12
	v_exp_f32_e32 v12, v12
	s_nop 0
	v_add_f32_e32 v12, 1.0, v12
	v_div_scale_f32 v13, s[46:47], v12, v12, 1.0
	v_rcp_f32_e32 v14, v13
	s_nop 0
	v_fma_f32 v16, -v13, v14, 1.0
	v_fmac_f32_e32 v14, v16, v14
	v_div_scale_f32 v16, vcc, 1.0, v12, 1.0
	v_mul_f32_e32 v17, v16, v14
	v_fma_f32 v18, -v13, v17, v16
	v_fmac_f32_e32 v17, v18, v14
	v_fma_f32 v13, -v13, v17, v16
	v_div_fmas_f32 v13, v13, v14, v17
	v_div_fixup_f32 v14, v13, v12, 1.0
	s_nop 1
	s_nop 1
	s_nop 1
	v_mov_b32_e32 v2, v242
	v_mul_f32_e32 v2, v14, v2
	v_mul_f32_e32 v2, 0x3fb8aa3b, v2
	v_exp_f32_e32 v2, v2
	s_nop 0
	v_fma_f32 v6, -v2, v2, 1.0
	v_max_f32_e32 v6, 0, v6
	v_cmp_gt_f32_e32 vcc, s69, v6
	v_mul_f32_e32 v12, 0x4f800000, v6
	s_nop 0
	v_cndmask_b32_e32 v6, v6, v12, vcc
	v_sqrt_f32_e32 v12, v6
	s_nop 0
	v_add_u32_e32 v13, -1, v12
	v_fma_f32 v14, -v13, v12, v6
	v_cmp_ge_f32_e64 s[46:47], 0, v14
	v_add_u32_e32 v14, 1, v12
	s_nop 0
	v_cndmask_b32_e64 v13, v12, v13, s[46:47]
	v_fma_f32 v12, -v14, v12, v6
	v_cmp_lt_f32_e64 s[46:47], 0, v12
	s_nop 1
	v_cndmask_b32_e64 v12, v13, v14, s[46:47]
	v_mul_f32_e32 v13, 0x37800000, v12
	v_cndmask_b32_e32 v12, v12, v13, vcc
	v_cmp_class_f32_e32 vcc, v6, v186
	s_nop 1
	v_cndmask_b32_e32 v6, v12, v6, vcc
	v_add_f32_e32 v12, v15, v19
	v_mul_f32_e32 v12, 0xbfb8aa3b, v12
	v_exp_f32_e32 v12, v12
	s_nop 0
	v_add_f32_e32 v12, 1.0, v12
	v_div_scale_f32 v13, s[46:47], v12, v12, 1.0
	v_rcp_f32_e32 v14, v13
	s_nop 0
	v_fma_f32 v15, -v13, v14, 1.0
	v_fmac_f32_e32 v14, v15, v14
	v_div_scale_f32 v15, vcc, 1.0, v12, 1.0
	v_mul_f32_e32 v16, v15, v14
	v_fma_f32 v17, -v13, v16, v15
	v_fmac_f32_e32 v16, v17, v14
	v_fma_f32 v13, -v13, v16, v15
	v_div_fmas_f32 v13, v13, v14, v16
	v_div_fixup_f32 v14, v13, v12, 1.0
	s_nop 1
	s_nop 1
	s_nop 1
	v_mov_b32_e32 v3, v243
	v_mul_f32_e32 v3, v14, v3
	v_mul_f32_e32 v3, 0x3fb8aa3b, v3
	v_exp_f32_e32 v3, v3
	s_nop 0
	v_fma_f32 v7, -v3, v3, 1.0
	v_max_f32_e32 v7, 0, v7
	v_cmp_gt_f32_e32 vcc, s69, v7
	v_mul_f32_e32 v12, 0x4f800000, v7
	s_nop 0
	v_cndmask_b32_e32 v7, v7, v12, vcc
	v_sqrt_f32_e32 v12, v7
	s_nop 0
	v_add_u32_e32 v13, -1, v12
	v_fma_f32 v14, -v13, v12, v7
	v_cmp_ge_f32_e64 s[46:47], 0, v14
	v_add_u32_e32 v14, 1, v12
	s_nop 0
	v_cndmask_b32_e64 v13, v12, v13, s[46:47]
	v_fma_f32 v12, -v14, v12, v7
	v_cmp_lt_f32_e64 s[46:47], 0, v12
	s_nop 1
	v_cndmask_b32_e64 v12, v13, v14, s[46:47]
	v_mul_f32_e32 v13, 0x37800000, v12
	v_cndmask_b32_e32 v12, v12, v13, vcc
	v_cmp_class_f32_e32 vcc, v7, v186
	s_nop 1
	v_cndmask_b32_e32 v7, v12, v7, vcc
	v_lshlrev_b64 v[12:13], 2, v[100:101]
	v_lshl_add_u64 v[14:15], v[56:57], 0, v[12:13]
	global_store_dwordx4 v[14:15], v[0:3], off
	v_div_scale_f32 v14, s[46:47], v9, v9, 1.0
	v_rcp_f32_e32 v15, v14
	v_lshl_add_u64 v[12:13], v[58:59], 0, v[12:13]
	v_fma_f32 v16, -v14, v15, 1.0
; DEVI float sigmoidf_(float x) { return 1.f / (1.f + __expf(-x)); }
; DEVI void gate_tile(const Params& P, int l, int pm, int q, char* smem, int tid) {
;     ...
;     for (int i = 0; i < 4; ++i) {
;       float r = sigmoidf_(rpa[i] + bav[i]);
;       float gi = sigmoidf_(gpa[i] + bxv[i]);
;       float a = __expf(-8.f * log1pf(__expf(-lmv[i])) * r);
;       av[i] = a;
;       uv[i] = sqrtf(fmaxf(1.f - a * a, 0.f)) * gi * xv[i];
;     }
;     *reinterpret_cast<float4*>(au0 + grow * 1024 + col) = make_float4(av[0], av[1], av[2], av[3]);
;     *reinterpret_cast<float4*>(au1 + grow * 1024 + col) = make_float4(uv[0], uv[1], uv[2], uv[3]);
;     *reinterpret_cast<float4*>(Tw + row * 128 + wcc * 64 + c32) = make_float4(av[0], av[1], av[2], av[3]);
;     *reinterpret_cast<float4*>(Tw + row * 128 + wcc * 64 + 32 + c32) = make_float4(uv[0], uv[1], uv[2], uv[3]);
	v_fmac_f32_e32 v15, v16, v15
	v_div_scale_f32 v16, vcc, 1.0, v9, 1.0
	v_mul_f32_e32 v17, v16, v15
	v_fma_f32 v18, -v14, v17, v16
	v_fmac_f32_e32 v17, v18, v15
	v_fma_f32 v14, -v14, v17, v16
	v_div_fmas_f32 v14, v14, v15, v17
	v_div_fixup_f32 v9, v14, v9, 1.0
	v_div_scale_f32 v14, s[46:47], v8, v8, 1.0
	v_rcp_f32_e32 v15, v14
	s_nop 0
	v_fma_f32 v16, -v14, v15, 1.0
	v_fmac_f32_e32 v15, v16, v15
	v_div_scale_f32 v16, vcc, 1.0, v8, 1.0
	v_mul_f32_e32 v17, v16, v15
	v_fma_f32 v18, -v14, v17, v16
	v_fmac_f32_e32 v17, v18, v15
	v_fma_f32 v14, -v14, v17, v16
	v_div_fmas_f32 v14, v14, v15, v17
	v_div_fixup_f32 v8, v14, v8, 1.0
	v_pk_mul_f32 v[4:5], v[8:9], v[4:5]
	v_pk_add_f32 v[8:9], v[10:11], 1.0 op_sel_hi:[1,0]
	v_pk_mul_f32 v[4:5], v[4:5], v[62:63]
	v_div_scale_f32 v10, s[46:47], v9, v9, 1.0
	v_rcp_f32_e32 v11, v10
	s_nop 0
	v_fma_f32 v14, -v10, v11, 1.0
	v_fmac_f32_e32 v11, v14, v11
	v_div_scale_f32 v14, vcc, 1.0, v9, 1.0
	v_mul_f32_e32 v15, v14, v11
	v_fma_f32 v16, -v10, v15, v14
	v_fmac_f32_e32 v15, v16, v11
	v_fma_f32 v10, -v10, v15, v14
	v_div_fmas_f32 v10, v10, v11, v15
	v_div_fixup_f32 v9, v10, v9, 1.0
	v_div_scale_f32 v10, s[46:47], v8, v8, 1.0
	v_rcp_f32_e32 v11, v10
	s_nop 0
	v_fma_f32 v14, -v10, v11, 1.0
	v_fmac_f32_e32 v11, v14, v11
	v_div_scale_f32 v14, vcc, 1.0, v8, 1.0
	v_mul_f32_e32 v15, v14, v11
	v_fma_f32 v16, -v10, v15, v14
	v_fmac_f32_e32 v15, v16, v11
	v_fma_f32 v10, -v10, v15, v14
	v_div_fmas_f32 v10, v10, v11, v15
	v_div_fixup_f32 v8, v10, v8, 1.0
	v_pk_mul_f32 v[6:7], v[8:9], v[6:7]
	s_nop 0
	v_pk_mul_f32 v[6:7], v[6:7], v[60:61]
	global_store_dwordx4 v[12:13], v[4:7], off
	ds_write_b128 v43, v[0:3]
	ds_write_b128 v43, v[4:7] offset:128
	v_add_u32_e32 v0, 0x200, v41
	v_ashrrev_i32_e32 v4, 4, v0
	v_ashrrev_i32_e32 v5, 31, v4
	v_lshl_or_b32 v43, v4, 9, v112
	v_lshlrev_b64 v[4:5], 10, v[4:5]
	v_lshl_add_u64 v[100:101], v[4:5], 0, s[54:55]
	v_lshl_add_u64 v[4:5], v[100:101], 1, v[48:49]
	ds_read_b128 v[12:15], v43
	ds_read_b128 v[0:3], v43 offset:128
	v_mov_b32_e32 v4, v224
	v_mov_b32_e32 v5, v225
	v_lshlrev_b32_e32 v62, 16, v4
	v_and_b32_e32 v63, 0xffff0000, v4
	v_lshlrev_b32_e32 v60, 16, v5
	v_and_b32_e32 v61, 0xffff0000, v5
	v_mov_b32_e32 v16, v212
	v_mov_b32_e32 v17, v213
	v_mov_b32_e32 v18, v214
	v_mov_b32_e32 v19, v215
	v_mov_b32_e32 v8, v216
	v_mov_b32_e32 v9, v217
	v_mov_b32_e32 v10, v218
	v_mov_b32_e32 v11, v219
	v_mov_b32_e32 v4, v220
	v_mov_b32_e32 v5, v221
	v_mov_b32_e32 v6, v222
	v_mov_b32_e32 v7, v223
	s_waitcnt lgkmcnt(1)
	v_add_f32_e32 v12, v12, v16
	v_mul_f32_e32 v12, 0xbfb8aa3b, v12
	v_exp_f32_e32 v12, v12
	s_waitcnt lgkmcnt(0)
	v_add_f32_e32 v0, v0, v8
	v_mul_f32_e32 v0, 0xbfb8aa3b, v0
	v_exp_f32_e32 v8, v0
	v_add_f32_e32 v12, 1.0, v12
	v_div_scale_f32 v16, s[46:47], v12, v12, 1.0
	v_rcp_f32_e32 v45, v16
	v_add_f32_e32 v1, v1, v9
	v_fma_f32 v47, -v16, v45, 1.0
	v_fmac_f32_e32 v45, v47, v45
	v_div_scale_f32 v47, vcc, 1.0, v12, 1.0
	v_mul_f32_e32 v113, v47, v45
	v_fma_f32 v114, -v16, v113, v47
	v_fmac_f32_e32 v113, v114, v45
	v_fma_f32 v16, -v16, v113, v47
	v_div_fmas_f32 v16, v16, v45, v113
	v_div_fixup_f32 v12, v16, v12, 1.0
	v_mul_f32_e32 v1, 0xbfb8aa3b, v1
	v_exp_f32_e32 v9, v1
	v_add_f32_e32 v2, v2, v10
	v_mul_f32_e32 v2, 0xbfb8aa3b, v2
	v_exp_f32_e32 v10, v2
	v_mov_b32_e32 v0, v240
	v_mul_f32_e32 v0, v12, v0
	v_mul_f32_e32 v0, 0x3fb8aa3b, v0
	v_exp_f32_e32 v0, v0
	v_add_f32_e32 v3, v3, v11
	v_fma_f32 v4, -v0, v0, 1.0
	v_max_f32_e32 v4, 0, v4
	v_cmp_gt_f32_e32 vcc, s69, v4
	v_mul_f32_e32 v12, 0x4f800000, v4
	s_nop 0
	v_cndmask_b32_e32 v4, v4, v12, vcc
	v_sqrt_f32_e32 v12, v4
	v_mul_f32_e32 v3, 0xbfb8aa3b, v3
	v_exp_f32_e32 v11, v3
	v_add_u32_e32 v16, -1, v12
	v_fma_f32 v45, -v16, v12, v4
	v_cmp_ge_f32_e64 s[46:47], 0, v45
	v_add_u32_e32 v45, 1, v12
	s_nop 0
	v_cndmask_b32_e64 v16, v12, v16, s[46:47]
	v_fma_f32 v12, -v45, v12, v4
	v_cmp_lt_f32_e64 s[46:47], 0, v12
	v_pk_add_f32 v[8:9], v[8:9], 1.0 op_sel_hi:[1,0]
	s_nop 0
	v_cndmask_b32_e64 v12, v16, v45, s[46:47]
	v_mul_f32_e32 v16, 0x37800000, v12
	v_cndmask_b32_e32 v12, v12, v16, vcc
	v_cmp_class_f32_e32 vcc, v4, v186
	s_nop 1
	v_cndmask_b32_e32 v4, v12, v4, vcc
	v_add_f32_e32 v12, v13, v17
	v_mul_f32_e32 v12, 0xbfb8aa3b, v12
	v_exp_f32_e32 v12, v12
	s_nop 0
	v_add_f32_e32 v12, 1.0, v12
	v_div_scale_f32 v13, s[46:47], v12, v12, 1.0
	v_rcp_f32_e32 v16, v13
	s_nop 0
	v_fma_f32 v17, -v13, v16, 1.0
	v_fmac_f32_e32 v16, v17, v16
	v_div_scale_f32 v17, vcc, 1.0, v12, 1.0
	v_mul_f32_e32 v45, v17, v16
	v_fma_f32 v47, -v13, v45, v17
	v_fmac_f32_e32 v45, v47, v16
	v_fma_f32 v13, -v13, v45, v17
	v_div_fmas_f32 v13, v13, v16, v45
	v_div_fixup_f32 v16, v13, v12, 1.0
	s_nop 1
	s_nop 1
	s_nop 1
	v_mov_b32_e32 v1, v241
	v_mul_f32_e32 v1, v16, v1
	v_mul_f32_e32 v1, 0x3fb8aa3b, v1
	v_exp_f32_e32 v1, v1
	s_nop 0
	v_fma_f32 v5, -v1, v1, 1.0
	v_max_f32_e32 v5, 0, v5
	v_cmp_gt_f32_e32 vcc, s69, v5
	v_mul_f32_e32 v12, 0x4f800000, v5
	s_nop 0
	v_cndmask_b32_e32 v5, v5, v12, vcc
	v_sqrt_f32_e32 v12, v5
	s_nop 0
	v_add_u32_e32 v13, -1, v12
	v_fma_f32 v16, -v13, v12, v5
	v_cmp_ge_f32_e64 s[46:47], 0, v16
	v_add_u32_e32 v16, 1, v12
	s_nop 0
	v_cndmask_b32_e64 v13, v12, v13, s[46:47]
	v_fma_f32 v12, -v16, v12, v5
	v_cmp_lt_f32_e64 s[46:47], 0, v12
	s_nop 1
	v_cndmask_b32_e64 v12, v13, v16, s[46:47]
	v_mul_f32_e32 v13, 0x37800000, v12
	v_cndmask_b32_e32 v12, v12, v13, vcc
	v_cmp_class_f32_e32 vcc, v5, v186
	s_nop 1
	v_cndmask_b32_e32 v5, v12, v5, vcc
	v_add_f32_e32 v12, v14, v18
	v_mul_f32_e32 v12, 0xbfb8aa3b, v12
	v_exp_f32_e32 v12, v12
	s_nop 0
	v_add_f32_e32 v12, 1.0, v12
	v_div_scale_f32 v13, s[46:47], v12, v12, 1.0
	v_rcp_f32_e32 v14, v13
	s_nop 0
	v_fma_f32 v16, -v13, v14, 1.0
; DEVI float sigmoidf_(float x) { return 1.f / (1.f + __expf(-x)); }
; DEVI void gate_tile(const Params& P, int l, int pm, int q, char* smem, int tid) {
;     ...
;     for (int i = 0; i < 4; ++i) {
;       float r = sigmoidf_(rpa[i] + bav[i]);
;       float gi = sigmoidf_(gpa[i] + bxv[i]);
;       float a = __expf(-8.f * log1pf(__expf(-lmv[i])) * r);
;       av[i] = a;
;       uv[i] = sqrtf(fmaxf(1.f - a * a, 0.f)) * gi * xv[i];
;     }
;     *reinterpret_cast<float4*>(au0 + grow * 1024 + col) = make_float4(av[0], av[1], av[2], av[3]);
;     *reinterpret_cast<float4*>(au1 + grow * 1024 + col) = make_float4(uv[0], uv[1], uv[2], uv[3]);
;     *reinterpret_cast<float4*>(Tw + row * 128 + wcc * 64 + c32) = make_float4(av[0], av[1], av[2], av[3]);
;     *reinterpret_cast<float4*>(Tw + row * 128 + wcc * 64 + 32 + c32) = make_float4(uv[0], uv[1], uv[2], uv[3]);
	v_fmac_f32_e32 v14, v16, v14
	v_div_scale_f32 v16, vcc, 1.0, v12, 1.0
	v_mul_f32_e32 v17, v16, v14
	v_fma_f32 v18, -v13, v17, v16
	v_fmac_f32_e32 v17, v18, v14
	v_fma_f32 v13, -v13, v17, v16
	v_div_fmas_f32 v13, v13, v14, v17
	v_div_fixup_f32 v14, v13, v12, 1.0
	s_nop 1
	s_nop 1
	s_nop 1
	v_mov_b32_e32 v2, v242
	v_mul_f32_e32 v2, v14, v2
	v_mul_f32_e32 v2, 0x3fb8aa3b, v2
	v_exp_f32_e32 v2, v2
	s_nop 0
	v_fma_f32 v6, -v2, v2, 1.0
	v_max_f32_e32 v6, 0, v6
	v_cmp_gt_f32_e32 vcc, s69, v6
	v_mul_f32_e32 v12, 0x4f800000, v6
	s_nop 0
	v_cndmask_b32_e32 v6, v6, v12, vcc
	v_sqrt_f32_e32 v12, v6
	s_nop 0
	v_add_u32_e32 v13, -1, v12
	v_fma_f32 v14, -v13, v12, v6
	v_cmp_ge_f32_e64 s[46:47], 0, v14
	v_add_u32_e32 v14, 1, v12
	s_nop 0
	v_cndmask_b32_e64 v13, v12, v13, s[46:47]
	v_fma_f32 v12, -v14, v12, v6
	v_cmp_lt_f32_e64 s[46:47], 0, v12
	s_nop 1
	v_cndmask_b32_e64 v12, v13, v14, s[46:47]
	v_mul_f32_e32 v13, 0x37800000, v12
	v_cndmask_b32_e32 v12, v12, v13, vcc
	v_cmp_class_f32_e32 vcc, v6, v186
	s_nop 1
	v_cndmask_b32_e32 v6, v12, v6, vcc
	v_add_f32_e32 v12, v15, v19
	v_mul_f32_e32 v12, 0xbfb8aa3b, v12
	v_exp_f32_e32 v12, v12
	s_nop 0
	v_add_f32_e32 v12, 1.0, v12
	v_div_scale_f32 v13, s[46:47], v12, v12, 1.0
	v_rcp_f32_e32 v14, v13
	s_nop 0
	v_fma_f32 v15, -v13, v14, 1.0
	v_fmac_f32_e32 v14, v15, v14
	v_div_scale_f32 v15, vcc, 1.0, v12, 1.0
	v_mul_f32_e32 v16, v15, v14
	v_fma_f32 v17, -v13, v16, v15
	v_fmac_f32_e32 v16, v17, v14
	v_fma_f32 v13, -v13, v16, v15
	v_div_fmas_f32 v13, v13, v14, v16
	v_div_fixup_f32 v14, v13, v12, 1.0
	s_nop 1
	s_nop 1
	s_nop 1
	v_mov_b32_e32 v3, v243
	v_mul_f32_e32 v3, v14, v3
	v_mul_f32_e32 v3, 0x3fb8aa3b, v3
	v_exp_f32_e32 v3, v3
	s_nop 0
	v_fma_f32 v7, -v3, v3, 1.0
	v_max_f32_e32 v7, 0, v7
	v_cmp_gt_f32_e32 vcc, s69, v7
	v_mul_f32_e32 v12, 0x4f800000, v7
	s_nop 0
	v_cndmask_b32_e32 v7, v7, v12, vcc
	v_sqrt_f32_e32 v12, v7
	s_nop 0
	v_add_u32_e32 v13, -1, v12
	v_fma_f32 v14, -v13, v12, v7
	v_cmp_ge_f32_e64 s[46:47], 0, v14
	v_add_u32_e32 v14, 1, v12
	s_nop 0
	v_cndmask_b32_e64 v13, v12, v13, s[46:47]
	v_fma_f32 v12, -v14, v12, v7
	v_cmp_lt_f32_e64 s[46:47], 0, v12
	s_nop 1
	v_cndmask_b32_e64 v12, v13, v14, s[46:47]
	v_mul_f32_e32 v13, 0x37800000, v12
	v_cndmask_b32_e32 v12, v12, v13, vcc
	v_cmp_class_f32_e32 vcc, v7, v186
	s_nop 1
	v_cndmask_b32_e32 v7, v12, v7, vcc
	v_lshlrev_b64 v[12:13], 2, v[100:101]
	v_lshl_add_u64 v[14:15], v[56:57], 0, v[12:13]
	global_store_dwordx4 v[14:15], v[0:3], off
	v_div_scale_f32 v14, s[46:47], v9, v9, 1.0
	v_rcp_f32_e32 v15, v14
	v_lshl_add_u64 v[12:13], v[58:59], 0, v[12:13]
	v_fma_f32 v16, -v14, v15, 1.0
	v_fmac_f32_e32 v15, v16, v15
	v_div_scale_f32 v16, vcc, 1.0, v9, 1.0
	v_mul_f32_e32 v17, v16, v15
	v_fma_f32 v18, -v14, v17, v16
	v_fmac_f32_e32 v17, v18, v15
	v_fma_f32 v14, -v14, v17, v16
	v_div_fmas_f32 v14, v14, v15, v17
	v_div_fixup_f32 v9, v14, v9, 1.0
	v_div_scale_f32 v14, s[46:47], v8, v8, 1.0
	v_rcp_f32_e32 v15, v14
	s_nop 0
	v_fma_f32 v16, -v14, v15, 1.0
	v_fmac_f32_e32 v15, v16, v15
	v_div_scale_f32 v16, vcc, 1.0, v8, 1.0
	v_mul_f32_e32 v17, v16, v15
	v_fma_f32 v18, -v14, v17, v16
	v_fmac_f32_e32 v17, v18, v15
	v_fma_f32 v14, -v14, v17, v16
	v_div_fmas_f32 v14, v14, v15, v17
	v_div_fixup_f32 v8, v14, v8, 1.0
	v_pk_mul_f32 v[4:5], v[8:9], v[4:5]
	v_pk_add_f32 v[8:9], v[10:11], 1.0 op_sel_hi:[1,0]
	v_pk_mul_f32 v[4:5], v[4:5], v[62:63]
	v_div_scale_f32 v10, s[46:47], v9, v9, 1.0
	v_rcp_f32_e32 v11, v10
	s_nop 0
	v_fma_f32 v14, -v10, v11, 1.0
	v_fmac_f32_e32 v11, v14, v11
	v_div_scale_f32 v14, vcc, 1.0, v9, 1.0
	v_mul_f32_e32 v15, v14, v11
	v_fma_f32 v16, -v10, v15, v14
	v_fmac_f32_e32 v15, v16, v11
	v_fma_f32 v10, -v10, v15, v14
	v_div_fmas_f32 v10, v10, v11, v15
	v_div_fixup_f32 v9, v10, v9, 1.0
	v_div_scale_f32 v10, s[46:47], v8, v8, 1.0
	v_rcp_f32_e32 v11, v10
	s_nop 0
	v_fma_f32 v14, -v10, v11, 1.0
	v_fmac_f32_e32 v11, v14, v11
	v_div_scale_f32 v14, vcc, 1.0, v8, 1.0
	v_mul_f32_e32 v15, v14, v11
	v_fma_f32 v16, -v10, v15, v14
	v_fmac_f32_e32 v15, v16, v11
	v_fma_f32 v10, -v10, v15, v14
	v_div_fmas_f32 v10, v10, v11, v15
	v_div_fixup_f32 v8, v10, v8, 1.0
	v_pk_mul_f32 v[6:7], v[8:9], v[6:7]
	s_nop 0
	v_pk_mul_f32 v[6:7], v[6:7], v[60:61]
	global_store_dwordx4 v[12:13], v[4:7], off
	ds_write_b128 v43, v[0:3]
	ds_write_b128 v43, v[4:7] offset:128
	v_add_u32_e32 v0, 0x300, v41
	v_ashrrev_i32_e32 v4, 4, v0
	v_ashrrev_i32_e32 v5, 31, v4
	v_lshl_or_b32 v41, v4, 9, v112
	v_lshlrev_b64 v[4:5], 10, v[4:5]
	v_lshl_add_u64 v[100:101], v[4:5], 0, s[54:55]
	v_lshl_add_u64 v[4:5], v[100:101], 1, v[48:49]
	ds_read_b128 v[12:15], v41
	ds_read_b128 v[0:3], v41 offset:128
	v_mov_b32_e32 v4, v226
	v_mov_b32_e32 v5, v227
	v_lshlrev_b32_e32 v62, 16, v4
	v_and_b32_e32 v63, 0xffff0000, v4
	v_lshlrev_b32_e32 v60, 16, v5
	v_and_b32_e32 v61, 0xffff0000, v5
	v_mov_b32_e32 v16, v212
	v_mov_b32_e32 v17, v213
	v_mov_b32_e32 v18, v214
	v_mov_b32_e32 v19, v215
	v_mov_b32_e32 v8, v216
	v_mov_b32_e32 v9, v217
	v_mov_b32_e32 v10, v218
	v_mov_b32_e32 v11, v219
	v_mov_b32_e32 v4, v220
	v_mov_b32_e32 v5, v221
	v_mov_b32_e32 v6, v222
	v_mov_b32_e32 v7, v223
	s_waitcnt lgkmcnt(1)
	v_add_f32_e32 v12, v12, v16
	v_mul_f32_e32 v12, 0xbfb8aa3b, v12
	v_exp_f32_e32 v12, v12
	s_waitcnt lgkmcnt(0)
; DEVI float sigmoidf_(float x) { return 1.f / (1.f + __expf(-x)); }
; DEVI void gate_tile(const Params& P, int l, int pm, int q, char* smem, int tid) {
;     ...
;     for (int i = 0; i < 4; ++i) {
;       float r = sigmoidf_(rpa[i] + bav[i]);
;       float gi = sigmoidf_(gpa[i] + bxv[i]);
;       float a = __expf(-8.f * log1pf(__expf(-lmv[i])) * r);
;       av[i] = a;
;       uv[i] = sqrtf(fmaxf(1.f - a * a, 0.f)) * gi * xv[i];
	v_add_f32_e32 v0, v0, v8
	v_mul_f32_e32 v0, 0xbfb8aa3b, v0
	v_exp_f32_e32 v8, v0
	v_add_f32_e32 v12, 1.0, v12
	v_div_scale_f32 v16, s[46:47], v12, v12, 1.0
	v_rcp_f32_e32 v43, v16
	v_add_f32_e32 v1, v1, v9
	v_fma_f32 v45, -v16, v43, 1.0
	v_fmac_f32_e32 v43, v45, v43
	v_div_scale_f32 v45, vcc, 1.0, v12, 1.0
	v_mul_f32_e32 v47, v45, v43
	v_fma_f32 v113, -v16, v47, v45
	v_fmac_f32_e32 v47, v113, v43
	v_fma_f32 v16, -v16, v47, v45
	v_div_fmas_f32 v16, v16, v43, v47
	v_div_fixup_f32 v12, v16, v12, 1.0
	v_mul_f32_e32 v1, 0xbfb8aa3b, v1
	v_exp_f32_e32 v9, v1
	v_add_f32_e32 v2, v2, v10
	v_mul_f32_e32 v2, 0xbfb8aa3b, v2
	v_exp_f32_e32 v10, v2
	v_mov_b32_e32 v0, v240
	v_mul_f32_e32 v0, v12, v0
	v_mul_f32_e32 v0, 0x3fb8aa3b, v0
	v_exp_f32_e32 v0, v0
	v_add_f32_e32 v3, v3, v11
	v_fma_f32 v4, -v0, v0, 1.0
	v_max_f32_e32 v4, 0, v4
	v_cmp_gt_f32_e32 vcc, s69, v4
	v_mul_f32_e32 v12, 0x4f800000, v4
	s_nop 0
	v_cndmask_b32_e32 v4, v4, v12, vcc
	v_sqrt_f32_e32 v12, v4
	v_mul_f32_e32 v3, 0xbfb8aa3b, v3
	v_exp_f32_e32 v11, v3
	v_add_u32_e32 v16, -1, v12
	v_fma_f32 v43, -v16, v12, v4
	v_cmp_ge_f32_e64 s[46:47], 0, v43
	v_add_u32_e32 v43, 1, v12
	s_nop 0
	v_cndmask_b32_e64 v16, v12, v16, s[46:47]
	v_fma_f32 v12, -v43, v12, v4
	v_cmp_lt_f32_e64 s[46:47], 0, v12
	v_pk_add_f32 v[8:9], v[8:9], 1.0 op_sel_hi:[1,0]
	s_nop 0
	v_cndmask_b32_e64 v12, v16, v43, s[46:47]
	v_mul_f32_e32 v16, 0x37800000, v12
	v_cndmask_b32_e32 v12, v12, v16, vcc
	v_cmp_class_f32_e32 vcc, v4, v186
	s_nop 1
	v_cndmask_b32_e32 v4, v12, v4, vcc
	v_add_f32_e32 v12, v13, v17
	v_mul_f32_e32 v12, 0xbfb8aa3b, v12
	v_exp_f32_e32 v12, v12
	s_nop 0
	v_add_f32_e32 v12, 1.0, v12
	v_div_scale_f32 v13, s[46:47], v12, v12, 1.0
	v_rcp_f32_e32 v16, v13
	s_nop 0
	v_fma_f32 v17, -v13, v16, 1.0
	v_fmac_f32_e32 v16, v17, v16
	v_div_scale_f32 v17, vcc, 1.0, v12, 1.0
	v_mul_f32_e32 v43, v17, v16
	v_fma_f32 v45, -v13, v43, v17
	v_fmac_f32_e32 v43, v45, v16
	v_fma_f32 v13, -v13, v43, v17
	v_div_fmas_f32 v13, v13, v16, v43
	v_div_fixup_f32 v16, v13, v12, 1.0
	s_nop 1
	s_nop 1
	s_nop 1
	v_mov_b32_e32 v1, v241
	v_mul_f32_e32 v1, v16, v1
	v_mul_f32_e32 v1, 0x3fb8aa3b, v1
	v_exp_f32_e32 v1, v1
	s_nop 0
	v_fma_f32 v5, -v1, v1, 1.0
	v_max_f32_e32 v5, 0, v5
	v_cmp_gt_f32_e32 vcc, s69, v5
	v_mul_f32_e32 v12, 0x4f800000, v5
	s_nop 0
	v_cndmask_b32_e32 v5, v5, v12, vcc
	v_sqrt_f32_e32 v12, v5
	s_nop 0
	v_add_u32_e32 v13, -1, v12
	v_fma_f32 v16, -v13, v12, v5
	v_cmp_ge_f32_e64 s[46:47], 0, v16
	v_add_u32_e32 v16, 1, v12
	s_nop 0
	v_cndmask_b32_e64 v13, v12, v13, s[46:47]
	v_fma_f32 v12, -v16, v12, v5
	v_cmp_lt_f32_e64 s[46:47], 0, v12
	s_nop 1
	v_cndmask_b32_e64 v12, v13, v16, s[46:47]
	v_mul_f32_e32 v13, 0x37800000, v12
	v_cndmask_b32_e32 v12, v12, v13, vcc
	v_cmp_class_f32_e32 vcc, v5, v186
	s_nop 1
	v_cndmask_b32_e32 v5, v12, v5, vcc
	v_add_f32_e32 v12, v14, v18
	v_mul_f32_e32 v12, 0xbfb8aa3b, v12
	v_exp_f32_e32 v12, v12
	s_nop 0
	v_add_f32_e32 v12, 1.0, v12
	v_div_scale_f32 v13, s[46:47], v12, v12, 1.0
	v_rcp_f32_e32 v14, v13
	s_nop 0
	v_fma_f32 v16, -v13, v14, 1.0
	v_fmac_f32_e32 v14, v16, v14
	v_div_scale_f32 v16, vcc, 1.0, v12, 1.0
	v_mul_f32_e32 v17, v16, v14
	v_fma_f32 v18, -v13, v17, v16
	v_fmac_f32_e32 v17, v18, v14
	v_fma_f32 v13, -v13, v17, v16
	v_div_fmas_f32 v13, v13, v14, v17
	v_div_fixup_f32 v14, v13, v12, 1.0
	s_nop 1
	s_nop 1
	s_nop 1
	v_mov_b32_e32 v2, v242
	v_mul_f32_e32 v2, v14, v2
	v_mul_f32_e32 v2, 0x3fb8aa3b, v2
	v_exp_f32_e32 v2, v2
	s_nop 0
	v_fma_f32 v6, -v2, v2, 1.0
	v_max_f32_e32 v6, 0, v6
	v_cmp_gt_f32_e32 vcc, s69, v6
	v_mul_f32_e32 v12, 0x4f800000, v6
	s_nop 0
	v_cndmask_b32_e32 v6, v6, v12, vcc
	v_sqrt_f32_e32 v12, v6
	s_nop 0
	v_add_u32_e32 v13, -1, v12
	v_fma_f32 v14, -v13, v12, v6
	v_cmp_ge_f32_e64 s[46:47], 0, v14
	v_add_u32_e32 v14, 1, v12
	s_nop 0
; DEVI float sigmoidf_(float x) { return 1.f / (1.f + __expf(-x)); }
; DEVI void gate_tile(const Params& P, int l, int pm, int q, char* smem, int tid) {
;     ...
;       float r = sigmoidf_(rpa[i] + bav[i]);
;       float gi = sigmoidf_(gpa[i] + bxv[i]);
;       float a = __expf(-8.f * log1pf(__expf(-lmv[i])) * r);
;       av[i] = a;
;       uv[i] = sqrtf(fmaxf(1.f - a * a, 0.f)) * gi * xv[i];
;     }
;     *reinterpret_cast<float4*>(au0 + grow * 1024 + col) = make_float4(av[0], av[1], av[2], av[3]);
;     *reinterpret_cast<float4*>(au1 + grow * 1024 + col) = make_float4(uv[0], uv[1], uv[2], uv[3]);
;     *reinterpret_cast<float4*>(Tw + row * 128 + wcc * 64 + c32) = make_float4(av[0], av[1], av[2], av[3]);
;     *reinterpret_cast<float4*>(Tw + row * 128 + wcc * 64 + 32 + c32) = make_float4(uv[0], uv[1], uv[2], uv[3]);
;   }
;   __syncthreads();
;   if (tid < 64) {
;     const int wcc = tid >> 5, c32 = tid & 31;
;     const float* ta = T + wcc * 64 + c32;
;     float Ap = 1.f, Hp = 0.f;
	v_cndmask_b32_e64 v13, v12, v13, s[46:47]
	v_fma_f32 v12, -v14, v12, v6
	v_cmp_lt_f32_e64 s[46:47], 0, v12
	s_nop 1
	v_cndmask_b32_e64 v12, v13, v14, s[46:47]
	v_mul_f32_e32 v13, 0x37800000, v12
	v_cndmask_b32_e32 v12, v12, v13, vcc
	v_cmp_class_f32_e32 vcc, v6, v186
	s_nop 1
	v_cndmask_b32_e32 v6, v12, v6, vcc
	v_add_f32_e32 v12, v15, v19
	v_mul_f32_e32 v12, 0xbfb8aa3b, v12
	v_exp_f32_e32 v12, v12
	s_nop 0
	v_add_f32_e32 v12, 1.0, v12
	v_div_scale_f32 v13, s[46:47], v12, v12, 1.0
	v_rcp_f32_e32 v14, v13
	s_nop 0
	v_fma_f32 v15, -v13, v14, 1.0
	v_fmac_f32_e32 v14, v15, v14
	v_div_scale_f32 v15, vcc, 1.0, v12, 1.0
	v_mul_f32_e32 v16, v15, v14
	v_fma_f32 v17, -v13, v16, v15
	v_fmac_f32_e32 v16, v17, v14
	v_fma_f32 v13, -v13, v16, v15
	v_div_fmas_f32 v13, v13, v14, v16
	v_div_fixup_f32 v14, v13, v12, 1.0
	s_nop 1
	s_nop 1
	s_nop 1
	v_mov_b32_e32 v3, v243
	v_mul_f32_e32 v3, v14, v3
	v_mul_f32_e32 v3, 0x3fb8aa3b, v3
	v_exp_f32_e32 v3, v3
	s_nop 0
	v_fma_f32 v7, -v3, v3, 1.0
	v_max_f32_e32 v7, 0, v7
	v_cmp_gt_f32_e32 vcc, s69, v7
	v_mul_f32_e32 v12, 0x4f800000, v7
	s_nop 0
	v_cndmask_b32_e32 v7, v7, v12, vcc
	v_sqrt_f32_e32 v12, v7
	s_nop 0
	v_add_u32_e32 v13, -1, v12
	v_fma_f32 v14, -v13, v12, v7
	v_cmp_ge_f32_e64 s[46:47], 0, v14
	v_add_u32_e32 v14, 1, v12
	s_nop 0
	v_cndmask_b32_e64 v13, v12, v13, s[46:47]
	v_fma_f32 v12, -v14, v12, v7
	v_cmp_lt_f32_e64 s[46:47], 0, v12
	s_nop 1
	v_cndmask_b32_e64 v12, v13, v14, s[46:47]
	v_mul_f32_e32 v13, 0x37800000, v12
	v_cndmask_b32_e32 v12, v12, v13, vcc
	v_cmp_class_f32_e32 vcc, v7, v186
	s_nop 1
	v_cndmask_b32_e32 v7, v12, v7, vcc
	v_lshlrev_b64 v[12:13], 2, v[100:101]
	v_lshl_add_u64 v[14:15], v[56:57], 0, v[12:13]
	global_store_dwordx4 v[14:15], v[0:3], off
	v_div_scale_f32 v14, s[46:47], v9, v9, 1.0
	v_rcp_f32_e32 v15, v14
	v_lshl_add_u64 v[12:13], v[58:59], 0, v[12:13]
	v_fma_f32 v16, -v14, v15, 1.0
	v_fmac_f32_e32 v15, v16, v15
	v_div_scale_f32 v16, vcc, 1.0, v9, 1.0
	v_mul_f32_e32 v17, v16, v15
	v_fma_f32 v18, -v14, v17, v16
	v_fmac_f32_e32 v17, v18, v15
	v_fma_f32 v14, -v14, v17, v16
	v_div_fmas_f32 v14, v14, v15, v17
	v_div_fixup_f32 v9, v14, v9, 1.0
	v_div_scale_f32 v14, s[46:47], v8, v8, 1.0
	v_rcp_f32_e32 v15, v14
	s_nop 0
	v_fma_f32 v16, -v14, v15, 1.0
	v_fmac_f32_e32 v15, v16, v15
	v_div_scale_f32 v16, vcc, 1.0, v8, 1.0
	v_mul_f32_e32 v17, v16, v15
	v_fma_f32 v18, -v14, v17, v16
	v_fmac_f32_e32 v17, v18, v15
	v_fma_f32 v14, -v14, v17, v16
	v_div_fmas_f32 v14, v14, v15, v17
	v_div_fixup_f32 v8, v14, v8, 1.0
	v_pk_mul_f32 v[4:5], v[8:9], v[4:5]
	v_pk_add_f32 v[8:9], v[10:11], 1.0 op_sel_hi:[1,0]
	v_pk_mul_f32 v[4:5], v[4:5], v[62:63]
	v_div_scale_f32 v10, s[46:47], v9, v9, 1.0
	v_rcp_f32_e32 v11, v10
	s_nop 0
	v_fma_f32 v14, -v10, v11, 1.0
	v_fmac_f32_e32 v11, v14, v11
	v_div_scale_f32 v14, vcc, 1.0, v9, 1.0
	v_mul_f32_e32 v15, v14, v11
	v_fma_f32 v16, -v10, v15, v14
	v_fmac_f32_e32 v15, v16, v11
	v_fma_f32 v10, -v10, v15, v14
	v_div_fmas_f32 v10, v10, v11, v15
	v_div_fixup_f32 v9, v10, v9, 1.0
	v_div_scale_f32 v10, s[46:47], v8, v8, 1.0
	v_rcp_f32_e32 v11, v10
	s_nop 0
	v_fma_f32 v14, -v10, v11, 1.0
	v_fmac_f32_e32 v11, v14, v11
	v_div_scale_f32 v14, vcc, 1.0, v8, 1.0
	v_mul_f32_e32 v15, v14, v11
	v_fma_f32 v16, -v10, v15, v14
	v_fmac_f32_e32 v15, v16, v11
	v_fma_f32 v10, -v10, v15, v14
	v_div_fmas_f32 v10, v10, v11, v15
	v_div_fixup_f32 v8, v10, v8, 1.0
	v_pk_mul_f32 v[6:7], v[8:9], v[6:7]
	s_nop 0
	v_pk_mul_f32 v[6:7], v[6:7], v[60:61]
	global_store_dwordx4 v[12:13], v[4:7], off
	ds_write_b128 v41, v[0:3]
	ds_write_b128 v41, v[4:7] offset:128
	s_cbranch_scc0 .LBB0_459
	s_waitcnt lgkmcnt(0)
	s_barrier
	s_and_saveexec_b64 s[46:47], s[44:45]
	s_cbranch_execz .LBB0_451
	v_mov_b32_e32 v1, 1.0
	v_mov_b32_e32 v2, 0
	s_mov_b32 s54, -16
	v_mov_b32_e32 v4, v111

; DEVI void phase7(const Params& P, int l, int pass, char* smem) {
;     ...
;       for (int q = 0; q < 16; ++q) {
;         const int id = tid + 256 * q, row = id >> 5, c4 = id & 31;
;         const int grow = pm * 128 + row, gcol = pn * 128 + c4 * 4;
;         float4 a = *reinterpret_cast<const float4*>(T + row * 128 + c4 * 4);
;         float4 xx = *reinterpret_cast<const float4*>(xrow(P, base + grow) + gcol);
;         *reinterpret_cast<float4*>(pre + (long)grow * 1024 + gcol) =
;             make_float4(ALPHA * xx.x + a.x, ALPHA * xx.y + a.y, ALPHA * xx.z + a.z, ALPHA * xx.w + a.w);
.LBB0_790:
	s_or_b64 exec, exec, s[42:43]
	v_lshl_or_b32 v11, v9, 12, v10
	v_lshl_add_u32 v9, v9, 5, v10
	v_cndmask_b32_e64 v10, v9, v11, s[40:41]
	v_mov_b32_e32 v9, s93
	v_mov_b32_e32 v11, s29
	v_cndmask_b32_e64 v13, v9, v11, s[40:41]
	v_mov_b32_e32 v9, s33
	v_mov_b32_e32 v11, s28
	v_cndmask_b32_e64 v12, v9, v11, s[40:41]
	v_ashrrev_i32_e32 v11, 31, v10
	v_lshlrev_b64 v[10:11], 12, v[10:11]
	v_lshl_add_u64 v[10:11], v[12:13], 0, v[10:11]
	v_lshl_add_u64 v[10:11], v[4:5], 2, v[10:11]
	v_ashrrev_i32_e32 v9, 31, v8
	s_addk_i32 s51, 0x800
	v_lshlrev_b64 v[8:9], 12, v[8:9]
	v_lshl_add_u64 v[8:9], v[6:7], 0, v[8:9]
	s_cmpk_eq_i32 s51, 0x1000
	s_waitcnt vmcnt(7) lgkmcnt(0)
	v_mov_b32_e32 v10, v232
	v_mov_b32_e32 v11, v233
	v_mov_b32_e32 v12, v234
	v_mov_b32_e32 v13, v235
	v_pk_fma_f32 v[0:1], v[10:11], s[92:93], v[0:1] op_sel_hi:[1,0,1]
	v_pk_fma_f32 v[2:3], v[12:13], s[92:93], v[2:3] op_sel_hi:[1,0,1]
	global_store_dwordx4 v[8:9], v[0:3], off
	s_cbranch_scc1 .LBB0_782

; DEVI TokInfo tokinfo(int it) {
;   TokInfo r;
;   if (it < 8192) { r.sample = 0; r.seq = it >> 12; r.t = it & 4095; }
;   else if (it < 8448) { int q = it - 8192; r.sample = 1; r.seq = q >> 5; r.t = q & 31; }
;   else { int q = it - 8448; r.sample = 0; r.seq = 2 + (q >> 12); r.t = q & 4095; }
;   return r;
; }
; DEVI float* xrow(const Params& P, int it) {
;   TokInfo ti = tokinfo(it);
;   return ti.sample ? P.out + OUT_YS + (long)(ti.seq * 32 + ti.t) * 1024
;                    : P.out + (long)(ti.seq * 4096 + ti.t) * 1024;
; DEVI void phase7(const Params& P, int l, int pass, char* smem) {
;     ...
;       for (int q = 0; q < 16; ++q) {
;         const int id = tid + 256 * q, row = id >> 5, c4 = id & 31;
;         const int grow = pm * 128 + row, gcol = pn * 128 + c4 * 4;
;         float4 a = *reinterpret_cast<const float4*>(T + row * 128 + c4 * 4);
;         float4 xx = *reinterpret_cast<const float4*>(xrow(P, base + grow) + gcol);
;         *reinterpret_cast<float4*>(pre + (long)grow * 1024 + gcol) =
;             make_float4(ALPHA * xx.x + a.x, ALPHA * xx.y + a.y, ALPHA * xx.z + a.z, ALPHA * xx.w + a.w);
.LBB0_797:
	s_andn2_saveexec_b64 s[42:43], s[42:43]
	v_ashrrev_i32_e32 v9, 12, v12
	v_and_b32_e32 v11, 0xfff, v12
	s_or_b64 s[40:41], s[40:41], exec
	s_or_b64 exec, exec, s[42:43]
	v_lshl_or_b32 v12, v9, 12, v11
	v_lshl_add_u32 v9, v9, 5, v11
	v_cndmask_b32_e64 v12, v9, v12, s[40:41]
	v_mov_b32_e32 v9, s93
	v_mov_b32_e32 v11, s29
	v_cndmask_b32_e64 v15, v9, v11, s[40:41]
	v_mov_b32_e32 v9, s33
	v_mov_b32_e32 v11, s28
	v_ashrrev_i32_e32 v13, 31, v12
	v_cndmask_b32_e64 v14, v9, v11, s[40:41]
	v_lshlrev_b64 v[12:13], 12, v[12:13]
	v_lshl_add_u64 v[12:13], v[14:15], 0, v[12:13]
	v_lshl_add_u64 v[12:13], v[4:5], 2, v[12:13]
	v_add_co_u32_e32 v236, vcc, 0x8000, v12
	s_nop 1
	v_addc_co_u32_e32 v237, vcc, 0, v13, vcc
	global_load_dwordx4 v[12:15], v[12:13], off
	global_load_dwordx4 v[208:211], v[236:237], off
	v_add_co_u32_e32 v236, vcc, 0x8000, v236
	s_nop 1
	v_addc_co_u32_e32 v237, vcc, 0, v237, vcc
	global_load_dwordx4 v[212:215], v[236:237], off
	v_add_co_u32_e32 v236, vcc, 0x8000, v236
	s_nop 1
	v_addc_co_u32_e32 v237, vcc, 0, v237, vcc
	global_load_dwordx4 v[216:219], v[236:237], off
	v_add_co_u32_e32 v236, vcc, 0x8000, v236
	s_nop 1
	v_addc_co_u32_e32 v237, vcc, 0, v237, vcc
	global_load_dwordx4 v[220:223], v[236:237], off
	v_add_co_u32_e32 v236, vcc, 0x8000, v236
	s_nop 1
	v_addc_co_u32_e32 v237, vcc, 0, v237, vcc
	global_load_dwordx4 v[224:227], v[236:237], off
	v_add_co_u32_e32 v236, vcc, 0x8000, v236
	s_nop 1
	v_addc_co_u32_e32 v237, vcc, 0, v237, vcc
	global_load_dwordx4 v[228:231], v[236:237], off
	v_add_co_u32_e32 v236, vcc, 0x8000, v236
	s_nop 1
	v_addc_co_u32_e32 v237, vcc, 0, v237, vcc
	global_load_dwordx4 v[232:235], v[236:237], off
	v_ashrrev_i32_e32 v9, 31, v8
	v_lshlrev_b64 v[8:9], 12, v[8:9]
	v_lshl_add_u64 v[8:9], v[6:7], 0, v[8:9]
	s_waitcnt vmcnt(7) lgkmcnt(0)
	v_pk_fma_f32 v[0:1], v[12:13], s[92:93], v[0:1] op_sel_hi:[1,0,1]
	v_pk_fma_f32 v[2:3], v[14:15], s[92:93], v[2:3] op_sel_hi:[1,0,1]
	v_add_u32_e32 v13, 0x100, v10
	global_store_dwordx4 v[8:9], v[0:3], off
	s_nop 1
	v_ashrrev_i32_e32 v0, 5, v13
	v_add_u32_e32 v8, s50, v0
	v_lshl_or_b32 v0, v0, 9, v156
	ds_read_b128 v[0:3], v0
	v_add_u32_e32 v12, s2, v8
	v_cmp_lt_i32_e32 vcc, s86, v12
	s_and_saveexec_b64 s[42:43], vcc
	s_xor_b64 s[42:43], exec, s[42:43]
	s_cbranch_execz .LBB0_805
	v_cmp_lt_u32_e32 vcc, s64, v12
	s_and_saveexec_b64 s[40:41], vcc
	s_xor_b64 s[40:41], exec, s[40:41]
	v_add_u32_e32 v11, 0xffffdf00, v12
	v_lshrrev_b32_e32 v9, 12, v11
	v_add_u32_e32 v9, 2, v9
	v_and_b32_e32 v11, 0xfff, v11
	s_or_saveexec_b64 s[44:45], s[40:41]
	s_mov_b64 s[40:41], -1
	s_xor_b64 exec, exec, s[44:45]
	v_add_u32_e32 v9, 0xffffe000, v12
	v_lshrrev_b32_e32 v9, 5, v9
	v_bfe_u32 v11, v13, 5, 5
	s_xor_b64 s[40:41], exec, -1
	s_or_b64 exec, exec, s[44:45]
.LBB0_805:
	s_andn2_saveexec_b64 s[42:43], s[42:43]
	v_ashrrev_i32_e32 v9, 12, v12
	v_and_b32_e32 v11, 0xfff, v12
	s_or_b64 s[40:41], s[40:41], exec
	s_or_b64 exec, exec, s[42:43]
	v_lshl_or_b32 v12, v9, 12, v11
	v_lshl_add_u32 v9, v9, 5, v11
	v_cndmask_b32_e64 v12, v9, v12, s[40:41]
	v_mov_b32_e32 v9, s93
	v_mov_b32_e32 v11, s29
	v_cndmask_b32_e64 v15, v9, v11, s[40:41]
	v_mov_b32_e32 v9, s33
	v_mov_b32_e32 v11, s28
	v_ashrrev_i32_e32 v13, 31, v12
	v_cndmask_b32_e64 v14, v9, v11, s[40:41]
	v_lshlrev_b64 v[12:13], 12, v[12:13]
	v_lshl_add_u64 v[12:13], v[14:15], 0, v[12:13]
	v_lshl_add_u64 v[12:13], v[4:5], 2, v[12:13]
	v_ashrrev_i32_e32 v9, 31, v8
	v_lshlrev_b64 v[8:9], 12, v[8:9]
	v_lshl_add_u64 v[8:9], v[6:7], 0, v[8:9]
	s_waitcnt vmcnt(7) lgkmcnt(0)
	v_mov_b32_e32 v12, v208
	v_mov_b32_e32 v13, v209
	v_mov_b32_e32 v14, v210
	v_mov_b32_e32 v15, v211
	v_pk_fma_f32 v[0:1], v[12:13], s[92:93], v[0:1] op_sel_hi:[1,0,1]
	v_pk_fma_f32 v[2:3], v[14:15], s[92:93], v[2:3] op_sel_hi:[1,0,1]
	v_add_u32_e32 v13, 0x200, v10
	global_store_dwordx4 v[8:9], v[0:3], off
	s_nop 1
	v_ashrrev_i32_e32 v0, 5, v13
	v_add_u32_e32 v8, s50, v0
	v_lshl_or_b32 v0, v0, 9, v156
	ds_read_b128 v[0:3], v0
	v_add_u32_e32 v12, s2, v8
	v_cmp_lt_i32_e32 vcc, s86, v12
	s_and_saveexec_b64 s[42:43], vcc
	s_xor_b64 s[42:43], exec, s[42:43]
	s_cbranch_execz .LBB0_813
	v_cmp_lt_u32_e32 vcc, s64, v12
	s_and_saveexec_b64 s[40:41], vcc
	s_xor_b64 s[40:41], exec, s[40:41]
	v_add_u32_e32 v11, 0xffffdf00, v12
	v_lshrrev_b32_e32 v9, 12, v11
	v_add_u32_e32 v9, 2, v9
	v_and_b32_e32 v11, 0xfff, v11
	s_or_saveexec_b64 s[44:45], s[40:41]
	s_mov_b64 s[40:41], -1
	s_xor_b64 exec, exec, s[44:45]
	v_add_u32_e32 v9, 0xffffe000, v12
	v_lshrrev_b32_e32 v9, 5, v9
	v_bfe_u32 v11, v13, 5, 5
	s_xor_b64 s[40:41], exec, -1
	s_or_b64 exec, exec, s[44:45]
.LBB0_813:
	s_andn2_saveexec_b64 s[42:43], s[42:43]
	v_ashrrev_i32_e32 v9, 12, v12
	v_and_b32_e32 v11, 0xfff, v12
	s_or_b64 s[40:41], s[40:41], exec
	s_or_b64 exec, exec, s[42:43]
	v_lshl_or_b32 v12, v9, 12, v11
	v_lshl_add_u32 v9, v9, 5, v11
	v_cndmask_b32_e64 v12, v9, v12, s[40:41]
	v_mov_b32_e32 v9, s93
	v_mov_b32_e32 v11, s29
	v_cndmask_b32_e64 v15, v9, v11, s[40:41]
	v_mov_b32_e32 v9, s33
	v_mov_b32_e32 v11, s28
	v_ashrrev_i32_e32 v13, 31, v12
	v_cndmask_b32_e64 v14, v9, v11, s[40:41]
	v_lshlrev_b64 v[12:13], 12, v[12:13]
	v_lshl_add_u64 v[12:13], v[14:15], 0, v[12:13]
	v_lshl_add_u64 v[12:13], v[4:5], 2, v[12:13]
	v_ashrrev_i32_e32 v9, 31, v8
	v_lshlrev_b64 v[8:9], 12, v[8:9]
	v_lshl_add_u64 v[8:9], v[6:7], 0, v[8:9]
	s_waitcnt vmcnt(7) lgkmcnt(0)
	v_mov_b32_e32 v12, v212
	v_mov_b32_e32 v13, v213
	v_mov_b32_e32 v14, v214
	v_mov_b32_e32 v15, v215
	v_pk_fma_f32 v[0:1], v[12:13], s[92:93], v[0:1] op_sel_hi:[1,0,1]
	v_pk_fma_f32 v[2:3], v[14:15], s[92:93], v[2:3] op_sel_hi:[1,0,1]
	v_add_u32_e32 v13, 0x300, v10
	global_store_dwordx4 v[8:9], v[0:3], off
	s_nop 1
	v_ashrrev_i32_e32 v0, 5, v13
	v_add_u32_e32 v8, s50, v0
	v_lshl_or_b32 v0, v0, 9, v156
	ds_read_b128 v[0:3], v0
	v_add_u32_e32 v12, s2, v8
	v_cmp_lt_i32_e32 vcc, s86, v12
	s_and_saveexec_b64 s[42:43], vcc
	s_xor_b64 s[42:43], exec, s[42:43]
	s_cbranch_execz .LBB0_821
	v_cmp_lt_u32_e32 vcc, s64, v12
	s_and_saveexec_b64 s[40:41], vcc
	s_xor_b64 s[40:41], exec, s[40:41]
	v_add_u32_e32 v11, 0xffffdf00, v12
	v_lshrrev_b32_e32 v9, 12, v11
	v_add_u32_e32 v9, 2, v9
	v_and_b32_e32 v11, 0xfff, v11
	s_or_saveexec_b64 s[44:45], s[40:41]
	s_mov_b64 s[40:41], -1
	s_xor_b64 exec, exec, s[44:45]
	v_add_u32_e32 v9, 0xffffe000, v12
	v_lshrrev_b32_e32 v9, 5, v9
	v_bfe_u32 v11, v13, 5, 5
	s_xor_b64 s[40:41], exec, -1
	s_or_b64 exec, exec, s[44:45]
; DEVI TokInfo tokinfo(int it) {
;   TokInfo r;
;   if (it < 8192) { r.sample = 0; r.seq = it >> 12; r.t = it & 4095; }
;   else if (it < 8448) { int q = it - 8192; r.sample = 1; r.seq = q >> 5; r.t = q & 31; }
;   else { int q = it - 8448; r.sample = 0; r.seq = 2 + (q >> 12); r.t = q & 4095; }
;   return r;
; }
; DEVI float* xrow(const Params& P, int it) {
;   TokInfo ti = tokinfo(it);
;   return ti.sample ? P.out + OUT_YS + (long)(ti.seq * 32 + ti.t) * 1024
;                    : P.out + (long)(ti.seq * 4096 + ti.t) * 1024;
; DEVI void phase7(const Params& P, int l, int pass, char* smem) {
;     ...
;       for (int q = 0; q < 16; ++q) {
;         const int id = tid + 256 * q, row = id >> 5, c4 = id & 31;
;         const int grow = pm * 128 + row, gcol = pn * 128 + c4 * 4;
;         float4 a = *reinterpret_cast<const float4*>(T + row * 128 + c4 * 4);
;         float4 xx = *reinterpret_cast<const float4*>(xrow(P, base + grow) + gcol);
;         *reinterpret_cast<float4*>(pre + (long)grow * 1024 + gcol) =
;             make_float4(ALPHA * xx.x + a.x, ALPHA * xx.y + a.y, ALPHA * xx.z + a.z, ALPHA * xx.w + a.w);
.LBB0_821:
	s_andn2_saveexec_b64 s[42:43], s[42:43]
	v_ashrrev_i32_e32 v9, 12, v12
	v_and_b32_e32 v11, 0xfff, v12
	s_or_b64 s[40:41], s[40:41], exec
	s_or_b64 exec, exec, s[42:43]
	v_lshl_or_b32 v12, v9, 12, v11
	v_lshl_add_u32 v9, v9, 5, v11
	v_cndmask_b32_e64 v12, v9, v12, s[40:41]
	v_mov_b32_e32 v9, s93
	v_mov_b32_e32 v11, s29
	v_cndmask_b32_e64 v15, v9, v11, s[40:41]
	v_mov_b32_e32 v9, s33
	v_mov_b32_e32 v11, s28
	v_ashrrev_i32_e32 v13, 31, v12
	v_cndmask_b32_e64 v14, v9, v11, s[40:41]
	v_lshlrev_b64 v[12:13], 12, v[12:13]
	v_lshl_add_u64 v[12:13], v[14:15], 0, v[12:13]
	v_lshl_add_u64 v[12:13], v[4:5], 2, v[12:13]
	v_ashrrev_i32_e32 v9, 31, v8
	v_lshlrev_b64 v[8:9], 12, v[8:9]
	v_lshl_add_u64 v[8:9], v[6:7], 0, v[8:9]
	s_waitcnt vmcnt(7) lgkmcnt(0)
	v_mov_b32_e32 v12, v216
	v_mov_b32_e32 v13, v217
	v_mov_b32_e32 v14, v218
	v_mov_b32_e32 v15, v219
	v_pk_fma_f32 v[0:1], v[12:13], s[92:93], v[0:1] op_sel_hi:[1,0,1]
	v_pk_fma_f32 v[2:3], v[14:15], s[92:93], v[2:3] op_sel_hi:[1,0,1]
	v_add_u32_e32 v13, 0x400, v10
	global_store_dwordx4 v[8:9], v[0:3], off
	s_nop 1
	v_ashrrev_i32_e32 v0, 5, v13
	v_add_u32_e32 v8, s50, v0
	v_lshl_or_b32 v0, v0, 9, v156
	ds_read_b128 v[0:3], v0
	v_add_u32_e32 v12, s2, v8
	v_cmp_lt_i32_e32 vcc, s86, v12
	s_and_saveexec_b64 s[42:43], vcc
	s_xor_b64 s[42:43], exec, s[42:43]
	s_cbranch_execz .LBB0_829
	v_cmp_lt_u32_e32 vcc, s64, v12
	s_and_saveexec_b64 s[40:41], vcc
	s_xor_b64 s[40:41], exec, s[40:41]
	v_add_u32_e32 v11, 0xffffdf00, v12
	v_lshrrev_b32_e32 v9, 12, v11
	v_add_u32_e32 v9, 2, v9
	v_and_b32_e32 v11, 0xfff, v11
	s_or_saveexec_b64 s[44:45], s[40:41]
	s_mov_b64 s[40:41], -1
	s_xor_b64 exec, exec, s[44:45]
	v_add_u32_e32 v9, 0xffffe000, v12
	v_lshrrev_b32_e32 v9, 5, v9
	v_bfe_u32 v11, v13, 5, 5
	s_xor_b64 s[40:41], exec, -1
	s_or_b64 exec, exec, s[44:45]
.LBB0_829:
	s_andn2_saveexec_b64 s[42:43], s[42:43]
	v_ashrrev_i32_e32 v9, 12, v12
	v_and_b32_e32 v11, 0xfff, v12
	s_or_b64 s[40:41], s[40:41], exec
	s_or_b64 exec, exec, s[42:43]
	v_lshl_or_b32 v12, v9, 12, v11
	v_lshl_add_u32 v9, v9, 5, v11
	v_cndmask_b32_e64 v12, v9, v12, s[40:41]
	v_mov_b32_e32 v9, s93
	v_mov_b32_e32 v11, s29
	v_cndmask_b32_e64 v15, v9, v11, s[40:41]
	v_mov_b32_e32 v9, s33
	v_mov_b32_e32 v11, s28
	v_ashrrev_i32_e32 v13, 31, v12
	v_cndmask_b32_e64 v14, v9, v11, s[40:41]
	v_lshlrev_b64 v[12:13], 12, v[12:13]
	v_lshl_add_u64 v[12:13], v[14:15], 0, v[12:13]
	v_lshl_add_u64 v[12:13], v[4:5], 2, v[12:13]
	v_ashrrev_i32_e32 v9, 31, v8
	v_lshlrev_b64 v[8:9], 12, v[8:9]
	v_lshl_add_u64 v[8:9], v[6:7], 0, v[8:9]
	s_waitcnt vmcnt(7) lgkmcnt(0)
	v_mov_b32_e32 v12, v220
	v_mov_b32_e32 v13, v221
	v_mov_b32_e32 v14, v222
	v_mov_b32_e32 v15, v223
	v_pk_fma_f32 v[0:1], v[12:13], s[92:93], v[0:1] op_sel_hi:[1,0,1]
	v_pk_fma_f32 v[2:3], v[14:15], s[92:93], v[2:3] op_sel_hi:[1,0,1]
	v_add_u32_e32 v13, 0x500, v10
	global_store_dwordx4 v[8:9], v[0:3], off
	s_nop 1
	v_ashrrev_i32_e32 v0, 5, v13
	v_add_u32_e32 v8, s50, v0
	v_lshl_or_b32 v0, v0, 9, v156
	ds_read_b128 v[0:3], v0
	v_add_u32_e32 v12, s2, v8
	v_cmp_lt_i32_e32 vcc, s86, v12
	s_and_saveexec_b64 s[42:43], vcc
	s_xor_b64 s[42:43], exec, s[42:43]
	s_cbranch_execz .LBB0_837
	v_cmp_lt_u32_e32 vcc, s64, v12
	s_and_saveexec_b64 s[40:41], vcc
	s_xor_b64 s[40:41], exec, s[40:41]
	v_add_u32_e32 v11, 0xffffdf00, v12
	v_lshrrev_b32_e32 v9, 12, v11
	v_add_u32_e32 v9, 2, v9
	v_and_b32_e32 v11, 0xfff, v11
	s_or_saveexec_b64 s[44:45], s[40:41]
	s_mov_b64 s[40:41], -1
	s_xor_b64 exec, exec, s[44:45]
	v_add_u32_e32 v9, 0xffffe000, v12
	v_lshrrev_b32_e32 v9, 5, v9
	v_bfe_u32 v11, v13, 5, 5
	s_xor_b64 s[40:41], exec, -1
	s_or_b64 exec, exec, s[44:45]
; DEVI TokInfo tokinfo(int it) {
;   TokInfo r;
;   if (it < 8192) { r.sample = 0; r.seq = it >> 12; r.t = it & 4095; }
;   else if (it < 8448) { int q = it - 8192; r.sample = 1; r.seq = q >> 5; r.t = q & 31; }
;   else { int q = it - 8448; r.sample = 0; r.seq = 2 + (q >> 12); r.t = q & 4095; }
;   return r;
; }
; DEVI float* xrow(const Params& P, int it) {
;   TokInfo ti = tokinfo(it);
;   return ti.sample ? P.out + OUT_YS + (long)(ti.seq * 32 + ti.t) * 1024
;                    : P.out + (long)(ti.seq * 4096 + ti.t) * 1024;
; DEVI void phase7(const Params& P, int l, int pass, char* smem) {
;     ...
;       for (int q = 0; q < 16; ++q) {
;         const int id = tid + 256 * q, row = id >> 5, c4 = id & 31;
;         const int grow = pm * 128 + row, gcol = pn * 128 + c4 * 4;
;         float4 a = *reinterpret_cast<const float4*>(T + row * 128 + c4 * 4);
;         float4 xx = *reinterpret_cast<const float4*>(xrow(P, base + grow) + gcol);
;         *reinterpret_cast<float4*>(pre + (long)grow * 1024 + gcol) =
;             make_float4(ALPHA * xx.x + a.x, ALPHA * xx.y + a.y, ALPHA * xx.z + a.z, ALPHA * xx.w + a.w);
.LBB0_837:
	s_andn2_saveexec_b64 s[42:43], s[42:43]
	v_ashrrev_i32_e32 v9, 12, v12
	v_and_b32_e32 v11, 0xfff, v12
	s_or_b64 s[40:41], s[40:41], exec
	s_or_b64 exec, exec, s[42:43]
	v_lshl_or_b32 v12, v9, 12, v11
	v_lshl_add_u32 v9, v9, 5, v11
	v_cndmask_b32_e64 v12, v9, v12, s[40:41]
	v_mov_b32_e32 v9, s93
	v_mov_b32_e32 v11, s29
	v_cndmask_b32_e64 v15, v9, v11, s[40:41]
	v_mov_b32_e32 v9, s33
	v_mov_b32_e32 v11, s28
	v_ashrrev_i32_e32 v13, 31, v12
	v_cndmask_b32_e64 v14, v9, v11, s[40:41]
	v_lshlrev_b64 v[12:13], 12, v[12:13]
	v_lshl_add_u64 v[12:13], v[14:15], 0, v[12:13]
	v_lshl_add_u64 v[12:13], v[4:5], 2, v[12:13]
	v_ashrrev_i32_e32 v9, 31, v8
	v_lshlrev_b64 v[8:9], 12, v[8:9]
	v_lshl_add_u64 v[8:9], v[6:7], 0, v[8:9]
	s_waitcnt vmcnt(7) lgkmcnt(0)
	v_mov_b32_e32 v12, v224
	v_mov_b32_e32 v13, v225
	v_mov_b32_e32 v14, v226
	v_mov_b32_e32 v15, v227
	v_pk_fma_f32 v[0:1], v[12:13], s[92:93], v[0:1] op_sel_hi:[1,0,1]
	v_pk_fma_f32 v[2:3], v[14:15], s[92:93], v[2:3] op_sel_hi:[1,0,1]
	v_add_u32_e32 v13, 0x600, v10
	global_store_dwordx4 v[8:9], v[0:3], off
	s_nop 1
	v_ashrrev_i32_e32 v0, 5, v13
	v_add_u32_e32 v8, s50, v0
	v_lshl_or_b32 v0, v0, 9, v156
	ds_read_b128 v[0:3], v0
	v_add_u32_e32 v12, s2, v8
	v_cmp_lt_i32_e32 vcc, s86, v12
	s_and_saveexec_b64 s[42:43], vcc
	s_xor_b64 s[42:43], exec, s[42:43]
	s_cbranch_execz .LBB0_845
	v_cmp_lt_u32_e32 vcc, s64, v12
	s_and_saveexec_b64 s[40:41], vcc
	s_xor_b64 s[40:41], exec, s[40:41]
	v_add_u32_e32 v11, 0xffffdf00, v12
	v_lshrrev_b32_e32 v9, 12, v11
	v_add_u32_e32 v9, 2, v9
	v_and_b32_e32 v11, 0xfff, v11
	s_or_saveexec_b64 s[44:45], s[40:41]
	s_mov_b64 s[40:41], -1
	s_xor_b64 exec, exec, s[44:45]
	v_add_u32_e32 v9, 0xffffe000, v12
	v_lshrrev_b32_e32 v9, 5, v9
	v_bfe_u32 v11, v13, 5, 5
	s_xor_b64 s[40:41], exec, -1
	s_or_b64 exec, exec, s[44:45]
.LBB0_845:
	s_andn2_saveexec_b64 s[42:43], s[42:43]
	v_ashrrev_i32_e32 v9, 12, v12
	v_and_b32_e32 v11, 0xfff, v12
	s_or_b64 s[40:41], s[40:41], exec
	s_or_b64 exec, exec, s[42:43]
	v_lshl_or_b32 v12, v9, 12, v11
	v_lshl_add_u32 v9, v9, 5, v11
	v_cndmask_b32_e64 v12, v9, v12, s[40:41]
	v_mov_b32_e32 v9, s93
	v_mov_b32_e32 v11, s29
	v_cndmask_b32_e64 v15, v9, v11, s[40:41]
	v_mov_b32_e32 v9, s33
	v_mov_b32_e32 v11, s28
	v_ashrrev_i32_e32 v13, 31, v12
	v_cndmask_b32_e64 v14, v9, v11, s[40:41]
	v_lshlrev_b64 v[12:13], 12, v[12:13]
	v_lshl_add_u64 v[12:13], v[14:15], 0, v[12:13]
	v_lshl_add_u64 v[12:13], v[4:5], 2, v[12:13]
	v_ashrrev_i32_e32 v9, 31, v8
	v_lshlrev_b64 v[8:9], 12, v[8:9]
	v_lshl_add_u64 v[8:9], v[6:7], 0, v[8:9]
	s_waitcnt vmcnt(7) lgkmcnt(0)
	v_mov_b32_e32 v12, v228
	v_mov_b32_e32 v13, v229
	v_mov_b32_e32 v14, v230
	v_mov_b32_e32 v15, v231
	v_pk_fma_f32 v[0:1], v[12:13], s[92:93], v[0:1] op_sel_hi:[1,0,1]
	v_pk_fma_f32 v[2:3], v[14:15], s[92:93], v[2:3] op_sel_hi:[1,0,1]
	v_add_u32_e32 v12, 0x700, v10
	global_store_dwordx4 v[8:9], v[0:3], off
	s_nop 1
	v_ashrrev_i32_e32 v0, 5, v12
	v_add_u32_e32 v8, s50, v0
	v_lshl_or_b32 v0, v0, 9, v156
	ds_read_b128 v[0:3], v0
	v_add_u32_e32 v11, s2, v8
	v_cmp_lt_i32_e32 vcc, s86, v11
	s_and_saveexec_b64 s[42:43], vcc
	s_xor_b64 s[42:43], exec, s[42:43]
	s_cbranch_execz .LBB0_853
	v_cmp_lt_u32_e32 vcc, s64, v11
	s_and_saveexec_b64 s[40:41], vcc
	s_xor_b64 s[40:41], exec, s[40:41]
	v_add_u32_e32 v10, 0xffffdf00, v11
	v_lshrrev_b32_e32 v9, 12, v10
	v_add_u32_e32 v9, 2, v9
	v_and_b32_e32 v10, 0xfff, v10
	s_or_saveexec_b64 s[44:45], s[40:41]
	s_mov_b64 s[40:41], -1
	s_xor_b64 exec, exec, s[44:45]
	v_add_u32_e32 v9, 0xffffe000, v11
	v_lshrrev_b32_e32 v9, 5, v9
	v_bfe_u32 v10, v12, 5, 5
	s_xor_b64 s[40:41], exec, -1
	s_or_b64 exec, exec, s[44:45]
